# scan waves at priority 1 instead of 3
# baseline (speedup 1.0000x reference)
; __device__ __forceinline__ void phase_scan(const Params& p, LAS unsigned char* lds) {
;     ...
;                     __builtin_amdgcn_s_setprio(3);
;                     const LAS float* sR = OPS + (n & 1) * SET_F + j0; const LAS float* sW = sR + 2048; const LAS float* sK = sW + 2048; const LAS float* sA = sK + 2048; const LAS float* sB = sA + 2048; const LAS float* sV = OPS + (n & 1) * SET_F + 10240;
;                     LAS float* sY = sYb + (n & 1) * 512;
;                     f32x4 a_ = *(const LAS f32x4*)(sA), w_ = *(const LAS f32x4*)(sW), b_ = *(const LAS f32x4*)(sB);
;                     f32x4 k_ = *(const LAS f32x4*)(sK), r_ = *(const LAS f32x4*)(sR);
;                     f32x4 vq[4];
; #pragma unroll
;                     for (int u = 0; u < 4; ++u) vq[u] = *(const LAS f32x4*)(sV + srow * 32 + 4 * u);
;                     f32x4 rp = r_;
; #pragma unroll
;                     for (int hb = 0; hb < 2; ++hb) {
;                         f32x4 vn[4];
; #pragma unroll
;                         for (int u = 0; u < 4; ++u) vn[u] = *(const LAS f32x4*)(sV + srow * 32 + ((16 * (hb + 1)) & 31) + 4 * u);
; #pragma unroll
;                         for (int u16 = 0; u16 < 16; ++u16) {
;                             const int s = 16 * hb + u16;
;                             const int sn = (s + 1) & 31;
;                             const f32x4 a_n = *(const LAS f32x4*)(sA + sn * 64), w_n = *(const LAS f32x4*)(sW + sn * 64), b_n = *(const LAS f32x4*)(sB + sn * 64);
;                             const f32x4 k_n = *(const LAS f32x4*)(sK + sn * 64), r_n = *(const LAS f32x4*)(sR + sn * 64);
;                             const float v = vq[u16 >> 2][u16 & 3];
;                             const f32x2 vv = {v, v};
;                             f32x2 pp = S01 * (f32x2){a_[0], a_[1]}; pp = S23 * (f32x2){a_[2], a_[3]} + pp;
;                             f32x2 yy = S01 * (f32x2){rp[0], rp[1]}; yy = S23 * (f32x2){rp[2], rp[3]} + yy;
;                             float sa = pp[0] + pp[1], y = yy[0] + yy[1];
;                             sa += dpp_f<0xB1>(sa); y += dpp_f<0xB1>(y);
;                             sa += dpp_f<0x4E>(sa); y += dpp_f<0x4E>(y);
;                             sa += dpp_f<0x141>(sa); y += dpp_f<0x141>(y);
;                             sa += dpp_f<0x140>(sa); y += dpp_f<0x140>(y);
;                             sY[((s - 1) & 31) * 16 + srow] = y;
.Lscan_wave_top:
	s_mov_b64 s[54:55], 0
	s_cmp_lt_i32 s81, 0
	s_cbranch_scc1 .LBB0_603
	s_setprio 1
	s_and_b32 s14, s81, 1
	s_mul_i32 s15, s14, 0xa800
	s_add_i32 s15, s15, 0x8800
	v_add_u32_e32 v124, s15, v178
	v_add_u32_e32 v125, s15, v179
	s_cmp_eq_u32 s81, 0
	s_cselect_b32 s14, 0xc000c000, -1
	s_mov_b32 s15, s14
	v_pk_mul_f32 v[114:115], v[166:167], v[22:23]
	v_pk_mul_f32 v[116:117], v[166:167], v[18:19]
	v_pk_fma_f32 v[114:115], v[164:165], v[24:25], v[114:115]
	v_pk_fma_f32 v[116:117], v[164:165], v[20:21], v[116:117]
	ds_read_b128 v[14:17], v124 offset:16384
	ds_read_b128 v[6:9], v124 offset:8192
	ds_read_b128 v[10:13], v124 offset:32768
	ds_read_b128 v[18:21], v124 offset:0
	ds_read_b128 v[2:5], v124 offset:24576
	ds_read_b128 v[82:85], v125 offset:40960
	v_add_f32_e32 v122, v114, v115
	v_pk_mul_f32 v[118:119], v[110:111], v[34:35] op_sel:[1,0]
	v_add_f32_e32 v214, v116, v117
	v_add_f32_dpp v122, v122, v122 quad_perm:[1,0,3,2] row_mask:0xf bank_mask:0xf bound_ctrl:1
	v_pk_mul_f32 v[120:121], v[110:111], v[36:37] op_sel:[1,0]
	v_add_f32_dpp v204, v204, v204 row_mirror row_mask:0xf bank_mask:0xf bound_ctrl:1
	v_add_f32_dpp v122, v122, v122 quad_perm:[2,3,0,1] row_mask:0xf bank_mask:0xf bound_ctrl:1
	v_pk_fma_f32 v[166:167], v[166:167], v[26:27], v[118:119]
	v_add_f32_dpp v204, v212, v212 row_mirror row_mask:0xf bank_mask:0xc bound_ctrl:1
	v_add_f32_dpp v122, v122, v122 row_half_mirror row_mask:0xf bank_mask:0xf bound_ctrl:1
	v_pk_fma_f32 v[164:165], v[164:165], v[28:29], v[120:121]
	v_add_f32_dpp v205, v205, v205 row_mirror row_mask:0xf bank_mask:0xf bound_ctrl:1
	v_add_f32_dpp v122, v122, v122 row_mirror row_mask:0xf bank_mask:0xf bound_ctrl:1
	v_add_f32_dpp v205, v213, v213 row_mirror row_mask:0xf bank_mask:0xc bound_ctrl:1
	v_add_f32_dpp v206, v206, v206 row_mirror row_mask:0xf bank_mask:0xf bound_ctrl:1
	v_pk_fma_f32 v[166:167], v[30:31], v[122:123], v[166:167] op_sel_hi:[1,0,1]
	v_pk_fma_f32 v[164:165], v[32:33], v[122:123], v[164:165] op_sel_hi:[1,0,1]
	v_add_f32_dpp v206, v214, v214 row_mirror row_mask:0xf bank_mask:0xc bound_ctrl:1
	v_pk_mul_f32 v[114:115], v[166:167], v[42:43]
	v_pk_mul_f32 v[116:117], v[166:167], v[38:39]
	v_pk_fma_f32 v[114:115], v[164:165], v[44:45], v[114:115]
	v_pk_fma_f32 v[116:117], v[164:165], v[40:41], v[116:117]
	ds_read_b128 v[34:37], v124 offset:16640
	ds_read_b128 v[26:29], v124 offset:8448
	ds_read_b128 v[30:33], v124 offset:33024
	ds_read_b128 v[38:41], v124 offset:256
	ds_read_b128 v[22:25], v124 offset:24832
	v_add_f32_e32 v122, v114, v115
	v_pk_mul_f32 v[118:119], v[112:113], v[54:55] op_sel_hi:[0,1]
	v_add_f32_e32 v215, v116, v117
	v_add_f32_dpp v122, v122, v122 quad_perm:[1,0,3,2] row_mask:0xf bank_mask:0xf bound_ctrl:1
	v_pk_mul_f32 v[120:121], v[112:113], v[56:57] op_sel_hi:[0,1]
	v_add_f32_dpp v207, v207, v207 row_mirror row_mask:0xf bank_mask:0xf bound_ctrl:1
	v_add_f32_dpp v122, v122, v122 quad_perm:[2,3,0,1] row_mask:0xf bank_mask:0xf bound_ctrl:1
	v_pk_fma_f32 v[166:167], v[166:167], v[46:47], v[118:119]
	v_add_f32_dpp v207, v215, v215 row_mirror row_mask:0xf bank_mask:0xc bound_ctrl:1
	v_add_f32_dpp v122, v122, v122 row_half_mirror row_mask:0xf bank_mask:0xf bound_ctrl:1
	v_pk_fma_f32 v[164:165], v[164:165], v[48:49], v[120:121]
	s_nop 0
	v_add_f32_dpp v122, v122, v122 row_mirror row_mask:0xf bank_mask:0xf bound_ctrl:1
	s_nop 0
	v_pk_fma_f32 v[166:167], v[50:51], v[122:123], v[166:167] op_sel_hi:[1,0,1]
	v_pk_fma_f32 v[164:165], v[52:53], v[122:123], v[164:165] op_sel_hi:[1,0,1]
	v_pk_mul_f32 v[114:115], v[166:167], v[62:63]
	v_pk_mul_f32 v[116:117], v[166:167], v[58:59]
	v_pk_fma_f32 v[114:115], v[164:165], v[64:65], v[114:115]
	v_pk_fma_f32 v[116:117], v[164:165], v[60:61], v[116:117]
	ds_read_b128 v[54:57], v124 offset:16896
	ds_read_b128 v[46:49], v124 offset:8704
	ds_read_b128 v[50:53], v124 offset:33280
	ds_read_b128 v[58:61], v124 offset:512
	ds_read_b128 v[42:45], v124 offset:25088
	v_add_f32_e32 v122, v114, v115
	v_pk_mul_f32 v[118:119], v[112:113], v[74:75] op_sel:[1,0]
	v_add_f32_e32 v216, v116, v117
	v_add_f32_dpp v122, v122, v122 quad_perm:[1,0,3,2] row_mask:0xf bank_mask:0xf bound_ctrl:1
	v_pk_mul_f32 v[120:121], v[112:113], v[76:77] op_sel:[1,0]
	v_add_f32_dpp v208, v208, v208 row_mirror row_mask:0xf bank_mask:0xf bound_ctrl:1
	v_add_f32_dpp v122, v122, v122 quad_perm:[2,3,0,1] row_mask:0xf bank_mask:0xf bound_ctrl:1
	v_pk_fma_f32 v[166:167], v[166:167], v[66:67], v[118:119]
	v_add_f32_dpp v208, v216, v216 row_mirror row_mask:0xf bank_mask:0xc bound_ctrl:1
	v_add_f32_dpp v122, v122, v122 row_half_mirror row_mask:0xf bank_mask:0xf bound_ctrl:1
	v_pk_fma_f32 v[164:165], v[164:165], v[68:69], v[120:121]
	s_nop 0
	v_add_f32_dpp v122, v122, v122 row_mirror row_mask:0xf bank_mask:0xf bound_ctrl:1
	s_nop 0
	v_pk_fma_f32 v[166:167], v[70:71], v[122:123], v[166:167] op_sel_hi:[1,0,1]
	v_pk_fma_f32 v[164:165], v[72:73], v[122:123], v[164:165] op_sel_hi:[1,0,1]
	s_waitcnt lgkmcnt(11)
	v_pk_mul_f32 v[114:115], v[166:167], v[2:3]
	v_pk_mul_f32 v[116:117], v[166:167], v[78:79]
	v_pk_fma_f32 v[114:115], v[164:165], v[4:5], v[114:115]
	v_pk_fma_f32 v[116:117], v[164:165], v[80:81], v[116:117]
	ds_read_b128 v[74:77], v124 offset:17152
	ds_read_b128 v[66:69], v124 offset:8960
	ds_read_b128 v[70:73], v124 offset:33536
	ds_read_b128 v[78:81], v124 offset:768
	ds_read_b128 v[62:65], v124 offset:25344
	v_add_f32_e32 v122, v114, v115
	s_waitcnt lgkmcnt(15)
; #define LAS __attribute__((address_space(3)))
; template <int CTRL> __device__ __forceinline__ float dpp_f(float x) { return __int_as_float(__builtin_amdgcn_update_dpp(0, __float_as_int(x), CTRL, 0xf, 0xf, false)); }
; __device__ __forceinline__ void phase_scan(const Params& p, LAS unsigned char* lds) {
;     ...
;                         for (int u16 = 0; u16 < 16; ++u16) {
;                             const int s = 16 * hb + u16;
;                             const int sn = (s + 1) & 31;
;                             const f32x4 a_n = *(const LAS f32x4*)(sA + sn * 64), w_n = *(const LAS f32x4*)(sW + sn * 64), b_n = *(const LAS f32x4*)(sB + sn * 64);
;                             const f32x4 k_n = *(const LAS f32x4*)(sK + sn * 64), r_n = *(const LAS f32x4*)(sR + sn * 64);
;                             const float v = vq[u16 >> 2][u16 & 3];
;                             const f32x2 vv = {v, v};
;                             f32x2 pp = S01 * (f32x2){a_[0], a_[1]}; pp = S23 * (f32x2){a_[2], a_[3]} + pp;
;                             f32x2 yy = S01 * (f32x2){rp[0], rp[1]}; yy = S23 * (f32x2){rp[2], rp[3]} + yy;
;                             float sa = pp[0] + pp[1], y = yy[0] + yy[1];
;                             sa += dpp_f<0xB1>(sa); y += dpp_f<0xB1>(y);
;                             sa += dpp_f<0x4E>(sa); y += dpp_f<0x4E>(y);
;                             sa += dpp_f<0x141>(sa); y += dpp_f<0x141>(y);
;                             sa += dpp_f<0x140>(sa); y += dpp_f<0x140>(y);
;                             sY[((s - 1) & 31) * 16 + srow] = y;
;                             const f32x2 sv = {sa, sa};
;                             S01 = S01 * (f32x2){w_[0], w_[1]} + vv * (f32x2){k_[0], k_[1]};
;                             S23 = S23 * (f32x2){w_[2], w_[3]} + vv * (f32x2){k_[2], k_[3]};
;                             S01 = sv * (f32x2){b_[0], b_[1]} + S01;
;                             S23 = sv * (f32x2){b_[2], b_[3]} + S23;
;                             rp = r_;
;                             a_ = a_n; w_ = w_n; b_ = b_n; k_ = k_n; r_ = r_n;
	v_pk_mul_f32 v[118:119], v[82:83], v[14:15] op_sel_hi:[0,1]
	v_add_f32_e32 v217, v116, v117
	v_add_f32_dpp v122, v122, v122 quad_perm:[1,0,3,2] row_mask:0xf bank_mask:0xf bound_ctrl:1
	v_pk_mul_f32 v[120:121], v[82:83], v[16:17] op_sel_hi:[0,1]
	v_add_f32_dpp v209, v209, v209 row_mirror row_mask:0xf bank_mask:0xf bound_ctrl:1
	v_add_f32_dpp v122, v122, v122 quad_perm:[2,3,0,1] row_mask:0xf bank_mask:0xf bound_ctrl:1
	v_pk_fma_f32 v[166:167], v[166:167], v[6:7], v[118:119]
	v_add_f32_dpp v209, v217, v217 row_mirror row_mask:0xf bank_mask:0xc bound_ctrl:1
	v_add_f32_dpp v122, v122, v122 row_half_mirror row_mask:0xf bank_mask:0xf bound_ctrl:1
	v_pk_fma_f32 v[164:165], v[164:165], v[8:9], v[120:121]
	s_nop 0
	v_add_f32_dpp v122, v122, v122 row_mirror row_mask:0xf bank_mask:0xf bound_ctrl:1
	s_nop 0
	v_pk_fma_f32 v[166:167], v[10:11], v[122:123], v[166:167] op_sel_hi:[1,0,1]
	v_pk_fma_f32 v[164:165], v[12:13], v[122:123], v[164:165] op_sel_hi:[1,0,1]
	s_waitcnt lgkmcnt(10)
	v_pk_mul_f32 v[114:115], v[166:167], v[22:23]
	v_pk_mul_f32 v[116:117], v[166:167], v[18:19]
	v_pk_fma_f32 v[114:115], v[164:165], v[24:25], v[114:115]
	v_pk_fma_f32 v[116:117], v[164:165], v[20:21], v[116:117]
	ds_read_b128 v[14:17], v124 offset:17408
	ds_read_b128 v[6:9], v124 offset:9216
	ds_read_b128 v[10:13], v124 offset:33792
	ds_read_b128 v[18:21], v124 offset:1024
	ds_read_b128 v[2:5], v124 offset:25600
	ds_read_b128 v[86:89], v125 offset:40976
	v_add_f32_e32 v122, v114, v115
	v_pk_mul_f32 v[118:119], v[82:83], v[34:35] op_sel:[1,0]
	v_add_f32_e32 v218, v116, v117
	v_add_f32_dpp v122, v122, v122 quad_perm:[1,0,3,2] row_mask:0xf bank_mask:0xf bound_ctrl:1
	v_pk_mul_f32 v[120:121], v[82:83], v[36:37] op_sel:[1,0]
	v_add_f32_dpp v210, v210, v210 row_mirror row_mask:0xf bank_mask:0xf bound_ctrl:1
	v_add_f32_dpp v122, v122, v122 quad_perm:[2,3,0,1] row_mask:0xf bank_mask:0xf bound_ctrl:1
	v_pk_fma_f32 v[166:167], v[166:167], v[26:27], v[118:119]
	v_add_f32_dpp v210, v218, v218 row_mirror row_mask:0xf bank_mask:0xc bound_ctrl:1
	v_add_f32_dpp v122, v122, v122 row_half_mirror row_mask:0xf bank_mask:0xf bound_ctrl:1
	v_pk_fma_f32 v[164:165], v[164:165], v[28:29], v[120:121]
	s_nop 0
	v_add_f32_dpp v122, v122, v122 row_mirror row_mask:0xf bank_mask:0xf bound_ctrl:1
	s_nop 0
	v_pk_fma_f32 v[166:167], v[30:31], v[122:123], v[166:167] op_sel_hi:[1,0,1]
	v_pk_fma_f32 v[164:165], v[32:33], v[122:123], v[164:165] op_sel_hi:[1,0,1]
	s_waitcnt lgkmcnt(11)
	v_pk_mul_f32 v[114:115], v[166:167], v[42:43]
	v_pk_mul_f32 v[116:117], v[166:167], v[38:39]
	v_pk_fma_f32 v[114:115], v[164:165], v[44:45], v[114:115]
	v_pk_fma_f32 v[116:117], v[164:165], v[40:41], v[116:117]
	ds_read_b128 v[34:37], v124 offset:17664
	ds_read_b128 v[26:29], v124 offset:9472
	ds_read_b128 v[30:33], v124 offset:34048
	ds_read_b128 v[38:41], v124 offset:1280
	ds_read_b128 v[22:25], v124 offset:25856
	v_add_f32_e32 v122, v114, v115
	v_pk_mul_f32 v[118:119], v[84:85], v[54:55] op_sel_hi:[0,1]
	v_add_f32_e32 v219, v116, v117
	v_add_f32_dpp v122, v122, v122 quad_perm:[1,0,3,2] row_mask:0xf bank_mask:0xf bound_ctrl:1
	v_pk_mul_f32 v[120:121], v[84:85], v[56:57] op_sel_hi:[0,1]
	v_add_f32_dpp v211, v211, v211 row_mirror row_mask:0xf bank_mask:0xf bound_ctrl:1
	v_add_f32_dpp v122, v122, v122 quad_perm:[2,3,0,1] row_mask:0xf bank_mask:0xf bound_ctrl:1
	v_pk_fma_f32 v[166:167], v[166:167], v[46:47], v[118:119]
	v_add_f32_dpp v211, v219, v219 row_mirror row_mask:0xf bank_mask:0xc bound_ctrl:1
	v_add_f32_dpp v122, v122, v122 row_half_mirror row_mask:0xf bank_mask:0xf bound_ctrl:1
	v_pk_fma_f32 v[164:165], v[164:165], v[48:49], v[120:121]
	v_add_f32_dpp v204, v204, v204 row_half_mirror row_mask:0xf bank_mask:0xf bound_ctrl:1
	v_add_f32_dpp v122, v122, v122 row_mirror row_mask:0xf bank_mask:0xf bound_ctrl:1
	v_add_f32_dpp v205, v205, v205 row_half_mirror row_mask:0xf bank_mask:0xf bound_ctrl:1
	v_add_f32_dpp v206, v206, v206 row_half_mirror row_mask:0xf bank_mask:0xf bound_ctrl:1
	v_pk_fma_f32 v[166:167], v[50:51], v[122:123], v[166:167] op_sel_hi:[1,0,1]
	v_pk_fma_f32 v[164:165], v[52:53], v[122:123], v[164:165] op_sel_hi:[1,0,1]
	v_add_f32_dpp v207, v207, v207 row_half_mirror row_mask:0xf bank_mask:0xf bound_ctrl:1
	v_add_f32_dpp v204, v208, v208 row_half_mirror row_mask:0xf bank_mask:0xa bound_ctrl:1
	s_waitcnt lgkmcnt(11)
	v_pk_mul_f32 v[114:115], v[166:167], v[62:63]
	v_pk_mul_f32 v[116:117], v[166:167], v[58:59]
	v_pk_fma_f32 v[114:115], v[164:165], v[64:65], v[114:115]
	v_pk_fma_f32 v[116:117], v[164:165], v[60:61], v[116:117]
	ds_read_b128 v[54:57], v124 offset:17920
	ds_read_b128 v[46:49], v124 offset:9728
	ds_read_b128 v[50:53], v124 offset:34304
	ds_read_b128 v[58:61], v124 offset:1536
	ds_read_b128 v[42:45], v124 offset:26112
	v_add_f32_e32 v122, v114, v115
	v_pk_mul_f32 v[118:119], v[84:85], v[74:75] op_sel:[1,0]
	v_add_f32_e32 v220, v116, v117
	v_add_f32_dpp v122, v122, v122 quad_perm:[1,0,3,2] row_mask:0xf bank_mask:0xf bound_ctrl:1
	v_pk_mul_f32 v[120:121], v[84:85], v[76:77] op_sel:[1,0]
	v_add_f32_dpp v205, v209, v209 row_half_mirror row_mask:0xf bank_mask:0xa bound_ctrl:1
	v_add_f32_dpp v122, v122, v122 quad_perm:[2,3,0,1] row_mask:0xf bank_mask:0xf bound_ctrl:1
	v_pk_fma_f32 v[166:167], v[166:167], v[66:67], v[118:119]
	v_add_f32_dpp v206, v210, v210 row_half_mirror row_mask:0xf bank_mask:0xa bound_ctrl:1
	v_add_f32_dpp v122, v122, v122 row_half_mirror row_mask:0xf bank_mask:0xf bound_ctrl:1
	v_pk_fma_f32 v[164:165], v[164:165], v[68:69], v[120:121]
	v_add_f32_dpp v207, v211, v211 row_half_mirror row_mask:0xf bank_mask:0xa bound_ctrl:1
	v_add_f32_dpp v122, v122, v122 row_mirror row_mask:0xf bank_mask:0xf bound_ctrl:1
	v_add_f32_dpp v204, v204, v204 quad_perm:[1,0,3,2] row_mask:0xf bank_mask:0xf bound_ctrl:1
	v_add_f32_dpp v205, v205, v205 quad_perm:[1,0,3,2] row_mask:0xf bank_mask:0xf bound_ctrl:1
	v_pk_fma_f32 v[166:167], v[70:71], v[122:123], v[166:167] op_sel_hi:[1,0,1]
	v_pk_fma_f32 v[164:165], v[72:73], v[122:123], v[164:165] op_sel_hi:[1,0,1]
	v_add_f32_dpp v206, v206, v206 quad_perm:[1,0,3,2] row_mask:0xf bank_mask:0xf bound_ctrl:1
	v_add_f32_dpp v207, v207, v207 quad_perm:[1,0,3,2] row_mask:0xf bank_mask:0xf bound_ctrl:1
	s_waitcnt lgkmcnt(11)
; #define LAS __attribute__((address_space(3)))
; template <int CTRL> __device__ __forceinline__ float dpp_f(float x) { return __int_as_float(__builtin_amdgcn_update_dpp(0, __float_as_int(x), CTRL, 0xf, 0xf, false)); }
; __device__ __forceinline__ void phase_scan(const Params& p, LAS unsigned char* lds) {
;     ...
;                         for (int u16 = 0; u16 < 16; ++u16) {
;                             const int s = 16 * hb + u16;
;                             const int sn = (s + 1) & 31;
;                             const f32x4 a_n = *(const LAS f32x4*)(sA + sn * 64), w_n = *(const LAS f32x4*)(sW + sn * 64), b_n = *(const LAS f32x4*)(sB + sn * 64);
;                             const f32x4 k_n = *(const LAS f32x4*)(sK + sn * 64), r_n = *(const LAS f32x4*)(sR + sn * 64);
;                             const float v = vq[u16 >> 2][u16 & 3];
;                             const f32x2 vv = {v, v};
;                             f32x2 pp = S01 * (f32x2){a_[0], a_[1]}; pp = S23 * (f32x2){a_[2], a_[3]} + pp;
;                             f32x2 yy = S01 * (f32x2){rp[0], rp[1]}; yy = S23 * (f32x2){rp[2], rp[3]} + yy;
;                             float sa = pp[0] + pp[1], y = yy[0] + yy[1];
;                             sa += dpp_f<0xB1>(sa); y += dpp_f<0xB1>(y);
;                             sa += dpp_f<0x4E>(sa); y += dpp_f<0x4E>(y);
;                             sa += dpp_f<0x141>(sa); y += dpp_f<0x141>(y);
;                             sa += dpp_f<0x140>(sa); y += dpp_f<0x140>(y);
;                             sY[((s - 1) & 31) * 16 + srow] = y;
;                             const f32x2 sv = {sa, sa};
;                             S01 = S01 * (f32x2){w_[0], w_[1]} + vv * (f32x2){k_[0], k_[1]};
;                             S23 = S23 * (f32x2){w_[2], w_[3]} + vv * (f32x2){k_[2], k_[3]};
;                             S01 = sv * (f32x2){b_[0], b_[1]} + S01;
;                             S23 = sv * (f32x2){b_[2], b_[3]} + S23;
;                             rp = r_;
;                             a_ = a_n; w_ = w_n; b_ = b_n; k_ = k_n; r_ = r_n;
	v_pk_mul_f32 v[114:115], v[166:167], v[2:3]
	v_pk_mul_f32 v[116:117], v[166:167], v[78:79]
	v_pk_fma_f32 v[114:115], v[164:165], v[4:5], v[114:115]
	v_pk_fma_f32 v[116:117], v[164:165], v[80:81], v[116:117]
	ds_read_b128 v[74:77], v124 offset:18176
	ds_read_b128 v[66:69], v124 offset:9984
	ds_read_b128 v[70:73], v124 offset:34560
	ds_read_b128 v[78:81], v124 offset:1792
	ds_read_b128 v[62:65], v124 offset:26368
	v_add_f32_e32 v122, v114, v115
	s_waitcnt lgkmcnt(15)
	v_pk_mul_f32 v[118:119], v[86:87], v[14:15] op_sel_hi:[0,1]
	v_add_f32_e32 v221, v116, v117
	v_add_f32_dpp v122, v122, v122 quad_perm:[1,0,3,2] row_mask:0xf bank_mask:0xf bound_ctrl:1
	v_pk_mul_f32 v[120:121], v[86:87], v[16:17] op_sel_hi:[0,1]
	v_add_f32_dpp v204, v204, v204 quad_perm:[2,3,0,1] row_mask:0xf bank_mask:0xf bound_ctrl:1
	v_add_f32_dpp v122, v122, v122 quad_perm:[2,3,0,1] row_mask:0xf bank_mask:0xf bound_ctrl:1
	v_pk_fma_f32 v[166:167], v[166:167], v[6:7], v[118:119]
	v_add_f32_dpp v205, v205, v205 quad_perm:[2,3,0,1] row_mask:0xf bank_mask:0xf bound_ctrl:1
	v_add_f32_dpp v122, v122, v122 row_half_mirror row_mask:0xf bank_mask:0xf bound_ctrl:1
	v_pk_fma_f32 v[164:165], v[164:165], v[8:9], v[120:121]
	v_add_f32_dpp v206, v206, v206 quad_perm:[2,3,0,1] row_mask:0xf bank_mask:0xf bound_ctrl:1
	v_add_f32_dpp v122, v122, v122 row_mirror row_mask:0xf bank_mask:0xf bound_ctrl:1
	v_add_f32_dpp v207, v207, v207 quad_perm:[2,3,0,1] row_mask:0xf bank_mask:0xf bound_ctrl:1
	v_cndmask_b32_e64 v202, v204, v205, s[34:35]
	v_pk_fma_f32 v[166:167], v[10:11], v[122:123], v[166:167] op_sel_hi:[1,0,1]
	v_pk_fma_f32 v[164:165], v[12:13], v[122:123], v[164:165] op_sel_hi:[1,0,1]
	v_cndmask_b32_e64 v202, v202, v206, s[56:57]
	v_cndmask_b32_e64 v202, v202, v207, s[98:99]
	s_waitcnt lgkmcnt(10)
	v_pk_mul_f32 v[114:115], v[166:167], v[22:23]
	v_pk_mul_f32 v[116:117], v[166:167], v[18:19]
	v_pk_fma_f32 v[114:115], v[164:165], v[24:25], v[114:115]
	v_pk_fma_f32 v[116:117], v[164:165], v[20:21], v[116:117]
	ds_read_b128 v[14:17], v124 offset:18432
	ds_read_b128 v[6:9], v124 offset:10240
	ds_read_b128 v[10:13], v124 offset:34816
	ds_read_b128 v[18:21], v124 offset:2048
	ds_read_b128 v[2:5], v124 offset:26624
	ds_read_b128 v[90:93], v125 offset:40992
	v_add_f32_e32 v122, v114, v115
	v_pk_mul_f32 v[118:119], v[86:87], v[34:35] op_sel:[1,0]
	v_add_f32_e32 v222, v116, v117
	v_add_f32_dpp v122, v122, v122 quad_perm:[1,0,3,2] row_mask:0xf bank_mask:0xf bound_ctrl:1
	v_pk_mul_f32 v[120:121], v[86:87], v[36:37] op_sel:[1,0]
	v_cvt_f16_f32_e32 v203, v202
	v_add_f32_dpp v122, v122, v122 quad_perm:[2,3,0,1] row_mask:0xf bank_mask:0xf bound_ctrl:1
	v_pk_fma_f32 v[166:167], v[166:167], v[26:27], v[118:119]
	s_mov_b64 exec, s[14:15]
	global_store_short v[128:129], v203, off
	s_mov_b64 exec, -1
	v_add_f32_dpp v122, v122, v122 row_half_mirror row_mask:0xf bank_mask:0xf bound_ctrl:1
	v_pk_fma_f32 v[164:165], v[164:165], v[28:29], v[120:121]
	v_lshl_add_u64 v[128:129], v[128:129], 0, s[100:101]
	v_add_f32_dpp v122, v122, v122 row_mirror row_mask:0xf bank_mask:0xf bound_ctrl:1
	s_nop 0
	v_pk_fma_f32 v[166:167], v[30:31], v[122:123], v[166:167] op_sel_hi:[1,0,1]
	v_pk_fma_f32 v[164:165], v[32:33], v[122:123], v[164:165] op_sel_hi:[1,0,1]
	s_waitcnt lgkmcnt(11)
	v_pk_mul_f32 v[114:115], v[166:167], v[42:43]
	v_pk_mul_f32 v[116:117], v[166:167], v[38:39]
	v_pk_fma_f32 v[114:115], v[164:165], v[44:45], v[114:115]
	v_pk_fma_f32 v[116:117], v[164:165], v[40:41], v[116:117]
	ds_read_b128 v[34:37], v124 offset:18688
	ds_read_b128 v[26:29], v124 offset:10496
	ds_read_b128 v[30:33], v124 offset:35072
	ds_read_b128 v[38:41], v124 offset:2304
	ds_read_b128 v[22:25], v124 offset:26880
	v_add_f32_e32 v122, v114, v115
	v_pk_mul_f32 v[118:119], v[88:89], v[54:55] op_sel_hi:[0,1]
	v_add_f32_e32 v223, v116, v117
	v_add_f32_dpp v122, v122, v122 quad_perm:[1,0,3,2] row_mask:0xf bank_mask:0xf bound_ctrl:1
	v_pk_mul_f32 v[120:121], v[88:89], v[56:57] op_sel_hi:[0,1]
	s_nop 0
	v_add_f32_dpp v122, v122, v122 quad_perm:[2,3,0,1] row_mask:0xf bank_mask:0xf bound_ctrl:1
	v_pk_fma_f32 v[166:167], v[166:167], v[46:47], v[118:119]
	s_nop 0
	v_add_f32_dpp v122, v122, v122 row_half_mirror row_mask:0xf bank_mask:0xf bound_ctrl:1
	v_pk_fma_f32 v[164:165], v[164:165], v[48:49], v[120:121]
	s_nop 0
	v_add_f32_dpp v122, v122, v122 row_mirror row_mask:0xf bank_mask:0xf bound_ctrl:1
	s_nop 0
	v_pk_fma_f32 v[166:167], v[50:51], v[122:123], v[166:167] op_sel_hi:[1,0,1]
	v_pk_fma_f32 v[164:165], v[52:53], v[122:123], v[164:165] op_sel_hi:[1,0,1]
	s_waitcnt lgkmcnt(11)
	v_pk_mul_f32 v[114:115], v[166:167], v[62:63]
	v_pk_mul_f32 v[116:117], v[166:167], v[58:59]
	v_pk_fma_f32 v[114:115], v[164:165], v[64:65], v[114:115]
	v_pk_fma_f32 v[116:117], v[164:165], v[60:61], v[116:117]
	ds_read_b128 v[54:57], v124 offset:18944
	ds_read_b128 v[46:49], v124 offset:10752
	ds_read_b128 v[50:53], v124 offset:35328
	ds_read_b128 v[58:61], v124 offset:2560
	ds_read_b128 v[42:45], v124 offset:27136
	v_add_f32_e32 v122, v114, v115
	v_pk_mul_f32 v[118:119], v[88:89], v[74:75] op_sel:[1,0]
	v_add_f32_e32 v224, v116, v117
	v_add_f32_dpp v122, v122, v122 quad_perm:[1,0,3,2] row_mask:0xf bank_mask:0xf bound_ctrl:1
	v_pk_mul_f32 v[120:121], v[88:89], v[76:77] op_sel:[1,0]
	s_nop 0
	v_add_f32_dpp v122, v122, v122 quad_perm:[2,3,0,1] row_mask:0xf bank_mask:0xf bound_ctrl:1
	v_pk_fma_f32 v[166:167], v[166:167], v[66:67], v[118:119]
	s_nop 0
	v_add_f32_dpp v122, v122, v122 row_half_mirror row_mask:0xf bank_mask:0xf bound_ctrl:1
	v_pk_fma_f32 v[164:165], v[164:165], v[68:69], v[120:121]
	s_nop 0
	v_add_f32_dpp v122, v122, v122 row_mirror row_mask:0xf bank_mask:0xf bound_ctrl:1
	s_nop 0
	v_pk_fma_f32 v[166:167], v[70:71], v[122:123], v[166:167] op_sel_hi:[1,0,1]
	v_pk_fma_f32 v[164:165], v[72:73], v[122:123], v[164:165] op_sel_hi:[1,0,1]
	s_waitcnt lgkmcnt(11)
; #define LAS __attribute__((address_space(3)))
; template <int CTRL> __device__ __forceinline__ float dpp_f(float x) { return __int_as_float(__builtin_amdgcn_update_dpp(0, __float_as_int(x), CTRL, 0xf, 0xf, false)); }
; __device__ __forceinline__ void phase_scan(const Params& p, LAS unsigned char* lds) {
;     ...
;                         for (int u16 = 0; u16 < 16; ++u16) {
;                             const int s = 16 * hb + u16;
;                             const int sn = (s + 1) & 31;
;                             const f32x4 a_n = *(const LAS f32x4*)(sA + sn * 64), w_n = *(const LAS f32x4*)(sW + sn * 64), b_n = *(const LAS f32x4*)(sB + sn * 64);
;                             const f32x4 k_n = *(const LAS f32x4*)(sK + sn * 64), r_n = *(const LAS f32x4*)(sR + sn * 64);
;                             const float v = vq[u16 >> 2][u16 & 3];
;                             const f32x2 vv = {v, v};
;                             f32x2 pp = S01 * (f32x2){a_[0], a_[1]}; pp = S23 * (f32x2){a_[2], a_[3]} + pp;
;                             f32x2 yy = S01 * (f32x2){rp[0], rp[1]}; yy = S23 * (f32x2){rp[2], rp[3]} + yy;
;                             float sa = pp[0] + pp[1], y = yy[0] + yy[1];
;                             sa += dpp_f<0xB1>(sa); y += dpp_f<0xB1>(y);
;                             sa += dpp_f<0x4E>(sa); y += dpp_f<0x4E>(y);
;                             sa += dpp_f<0x141>(sa); y += dpp_f<0x141>(y);
;                             sa += dpp_f<0x140>(sa); y += dpp_f<0x140>(y);
;                             sY[((s - 1) & 31) * 16 + srow] = y;
;                             const f32x2 sv = {sa, sa};
;                             S01 = S01 * (f32x2){w_[0], w_[1]} + vv * (f32x2){k_[0], k_[1]};
;                             S23 = S23 * (f32x2){w_[2], w_[3]} + vv * (f32x2){k_[2], k_[3]};
;                             S01 = sv * (f32x2){b_[0], b_[1]} + S01;
;                             S23 = sv * (f32x2){b_[2], b_[3]} + S23;
;                             rp = r_;
;                             a_ = a_n; w_ = w_n; b_ = b_n; k_ = k_n; r_ = r_n;
	v_pk_mul_f32 v[114:115], v[166:167], v[2:3]
	v_pk_mul_f32 v[116:117], v[166:167], v[78:79]
	v_pk_fma_f32 v[114:115], v[164:165], v[4:5], v[114:115]
	v_pk_fma_f32 v[116:117], v[164:165], v[80:81], v[116:117]
	ds_read_b128 v[74:77], v124 offset:19200
	ds_read_b128 v[66:69], v124 offset:11008
	ds_read_b128 v[70:73], v124 offset:35584
	ds_read_b128 v[78:81], v124 offset:2816
	ds_read_b128 v[62:65], v124 offset:27392
	v_add_f32_e32 v122, v114, v115
	s_waitcnt lgkmcnt(15)
	v_pk_mul_f32 v[118:119], v[90:91], v[14:15] op_sel_hi:[0,1]
	v_add_f32_e32 v225, v116, v117
	v_add_f32_dpp v122, v122, v122 quad_perm:[1,0,3,2] row_mask:0xf bank_mask:0xf bound_ctrl:1
	v_pk_mul_f32 v[120:121], v[90:91], v[16:17] op_sel_hi:[0,1]
	s_nop 0
	v_add_f32_dpp v122, v122, v122 quad_perm:[2,3,0,1] row_mask:0xf bank_mask:0xf bound_ctrl:1
	v_pk_fma_f32 v[166:167], v[166:167], v[6:7], v[118:119]
	s_nop 0
	v_add_f32_dpp v122, v122, v122 row_half_mirror row_mask:0xf bank_mask:0xf bound_ctrl:1
	v_pk_fma_f32 v[164:165], v[164:165], v[8:9], v[120:121]
	s_nop 0
	v_add_f32_dpp v122, v122, v122 row_mirror row_mask:0xf bank_mask:0xf bound_ctrl:1
	s_nop 0
	v_pk_fma_f32 v[166:167], v[10:11], v[122:123], v[166:167] op_sel_hi:[1,0,1]
	v_pk_fma_f32 v[164:165], v[12:13], v[122:123], v[164:165] op_sel_hi:[1,0,1]
	s_waitcnt lgkmcnt(10)
	v_pk_mul_f32 v[114:115], v[166:167], v[22:23]
	v_pk_mul_f32 v[116:117], v[166:167], v[18:19]
	v_pk_fma_f32 v[114:115], v[164:165], v[24:25], v[114:115]
	v_pk_fma_f32 v[116:117], v[164:165], v[20:21], v[116:117]
	ds_read_b128 v[14:17], v124 offset:19456
	ds_read_b128 v[6:9], v124 offset:11264
	ds_read_b128 v[10:13], v124 offset:35840
	ds_read_b128 v[18:21], v124 offset:3072
	ds_read_b128 v[2:5], v124 offset:27648
	ds_read_b128 v[94:97], v125 offset:41008
	v_add_f32_e32 v122, v114, v115
	v_pk_mul_f32 v[118:119], v[90:91], v[34:35] op_sel:[1,0]
	v_add_f32_e32 v226, v116, v117
	v_add_f32_dpp v122, v122, v122 quad_perm:[1,0,3,2] row_mask:0xf bank_mask:0xf bound_ctrl:1
	v_pk_mul_f32 v[120:121], v[90:91], v[36:37] op_sel:[1,0]
	s_nop 0
	v_add_f32_dpp v122, v122, v122 quad_perm:[2,3,0,1] row_mask:0xf bank_mask:0xf bound_ctrl:1
	v_pk_fma_f32 v[166:167], v[166:167], v[26:27], v[118:119]
	s_nop 0
	v_add_f32_dpp v122, v122, v122 row_half_mirror row_mask:0xf bank_mask:0xf bound_ctrl:1
	v_pk_fma_f32 v[164:165], v[164:165], v[28:29], v[120:121]
	s_nop 0
	v_add_f32_dpp v122, v122, v122 row_mirror row_mask:0xf bank_mask:0xf bound_ctrl:1
	s_nop 0
	v_pk_fma_f32 v[166:167], v[30:31], v[122:123], v[166:167] op_sel_hi:[1,0,1]
	v_pk_fma_f32 v[164:165], v[32:33], v[122:123], v[164:165] op_sel_hi:[1,0,1]
	s_waitcnt lgkmcnt(11)
	v_pk_mul_f32 v[114:115], v[166:167], v[42:43]
	v_pk_mul_f32 v[116:117], v[166:167], v[38:39]
	v_pk_fma_f32 v[114:115], v[164:165], v[44:45], v[114:115]
	v_pk_fma_f32 v[116:117], v[164:165], v[40:41], v[116:117]
	ds_read_b128 v[34:37], v124 offset:19712
	ds_read_b128 v[26:29], v124 offset:11520
	ds_read_b128 v[30:33], v124 offset:36096
	ds_read_b128 v[38:41], v124 offset:3328
	ds_read_b128 v[22:25], v124 offset:27904
	v_add_f32_e32 v122, v114, v115
	v_pk_mul_f32 v[118:119], v[92:93], v[54:55] op_sel_hi:[0,1]
	v_add_f32_e32 v227, v116, v117
	v_add_f32_dpp v122, v122, v122 quad_perm:[1,0,3,2] row_mask:0xf bank_mask:0xf bound_ctrl:1
	v_pk_mul_f32 v[120:121], v[92:93], v[56:57] op_sel_hi:[0,1]
	s_nop 0
	v_add_f32_dpp v122, v122, v122 quad_perm:[2,3,0,1] row_mask:0xf bank_mask:0xf bound_ctrl:1
	v_pk_fma_f32 v[166:167], v[166:167], v[46:47], v[118:119]
	s_nop 0
	v_add_f32_dpp v122, v122, v122 row_half_mirror row_mask:0xf bank_mask:0xf bound_ctrl:1
	v_pk_fma_f32 v[164:165], v[164:165], v[48:49], v[120:121]
	s_nop 0
	v_add_f32_dpp v122, v122, v122 row_mirror row_mask:0xf bank_mask:0xf bound_ctrl:1
	s_nop 0
	v_pk_fma_f32 v[166:167], v[50:51], v[122:123], v[166:167] op_sel_hi:[1,0,1]
	v_pk_fma_f32 v[164:165], v[52:53], v[122:123], v[164:165] op_sel_hi:[1,0,1]
	s_waitcnt lgkmcnt(11)
	v_pk_mul_f32 v[114:115], v[166:167], v[62:63]
	v_pk_mul_f32 v[116:117], v[166:167], v[58:59]
	v_pk_fma_f32 v[114:115], v[164:165], v[64:65], v[114:115]
	v_pk_fma_f32 v[116:117], v[164:165], v[60:61], v[116:117]
	ds_read_b128 v[54:57], v124 offset:19968
	ds_read_b128 v[46:49], v124 offset:11776
	ds_read_b128 v[50:53], v124 offset:36352
	ds_read_b128 v[58:61], v124 offset:3584
	ds_read_b128 v[42:45], v124 offset:28160
	v_add_f32_e32 v122, v114, v115
	v_pk_mul_f32 v[118:119], v[92:93], v[74:75] op_sel:[1,0]
	v_add_f32_e32 v228, v116, v117
	v_add_f32_dpp v122, v122, v122 quad_perm:[1,0,3,2] row_mask:0xf bank_mask:0xf bound_ctrl:1
	v_pk_mul_f32 v[120:121], v[92:93], v[76:77] op_sel:[1,0]
	v_add_f32_dpp v220, v220, v220 row_mirror row_mask:0xf bank_mask:0xf bound_ctrl:1
	v_add_f32_dpp v122, v122, v122 quad_perm:[2,3,0,1] row_mask:0xf bank_mask:0xf bound_ctrl:1
	v_pk_fma_f32 v[166:167], v[166:167], v[66:67], v[118:119]
	v_add_f32_dpp v220, v228, v228 row_mirror row_mask:0xf bank_mask:0xc bound_ctrl:1
	v_add_f32_dpp v122, v122, v122 row_half_mirror row_mask:0xf bank_mask:0xf bound_ctrl:1
	v_pk_fma_f32 v[164:165], v[164:165], v[68:69], v[120:121]
	s_nop 0
	v_add_f32_dpp v122, v122, v122 row_mirror row_mask:0xf bank_mask:0xf bound_ctrl:1
	s_nop 0
	v_pk_fma_f32 v[166:167], v[70:71], v[122:123], v[166:167] op_sel_hi:[1,0,1]
	v_pk_fma_f32 v[164:165], v[72:73], v[122:123], v[164:165] op_sel_hi:[1,0,1]
	s_waitcnt lgkmcnt(11)
	v_pk_mul_f32 v[114:115], v[166:167], v[2:3]
	v_pk_mul_f32 v[116:117], v[166:167], v[78:79]
	v_pk_fma_f32 v[114:115], v[164:165], v[4:5], v[114:115]
	v_pk_fma_f32 v[116:117], v[164:165], v[80:81], v[116:117]
	ds_read_b128 v[74:77], v124 offset:20224
	ds_read_b128 v[66:69], v124 offset:12032
	ds_read_b128 v[70:73], v124 offset:36608
	ds_read_b128 v[78:81], v124 offset:3840
	ds_read_b128 v[62:65], v124 offset:28416
	v_add_f32_e32 v122, v114, v115
	s_waitcnt lgkmcnt(15)
; #define LAS __attribute__((address_space(3)))
; template <int CTRL> __device__ __forceinline__ float dpp_f(float x) { return __int_as_float(__builtin_amdgcn_update_dpp(0, __float_as_int(x), CTRL, 0xf, 0xf, false)); }
; __device__ __forceinline__ void phase_scan(const Params& p, LAS unsigned char* lds) {
;     ...
;                         for (int u16 = 0; u16 < 16; ++u16) {
;                             const int s = 16 * hb + u16;
;                             const int sn = (s + 1) & 31;
;                             const f32x4 a_n = *(const LAS f32x4*)(sA + sn * 64), w_n = *(const LAS f32x4*)(sW + sn * 64), b_n = *(const LAS f32x4*)(sB + sn * 64);
;                             const f32x4 k_n = *(const LAS f32x4*)(sK + sn * 64), r_n = *(const LAS f32x4*)(sR + sn * 64);
;                             const float v = vq[u16 >> 2][u16 & 3];
;                             const f32x2 vv = {v, v};
;                             f32x2 pp = S01 * (f32x2){a_[0], a_[1]}; pp = S23 * (f32x2){a_[2], a_[3]} + pp;
;                             f32x2 yy = S01 * (f32x2){rp[0], rp[1]}; yy = S23 * (f32x2){rp[2], rp[3]} + yy;
;                             float sa = pp[0] + pp[1], y = yy[0] + yy[1];
;                             sa += dpp_f<0xB1>(sa); y += dpp_f<0xB1>(y);
;                             sa += dpp_f<0x4E>(sa); y += dpp_f<0x4E>(y);
;                             sa += dpp_f<0x141>(sa); y += dpp_f<0x141>(y);
;                             sa += dpp_f<0x140>(sa); y += dpp_f<0x140>(y);
;                             sY[((s - 1) & 31) * 16 + srow] = y;
;                             const f32x2 sv = {sa, sa};
;                             S01 = S01 * (f32x2){w_[0], w_[1]} + vv * (f32x2){k_[0], k_[1]};
;                             S23 = S23 * (f32x2){w_[2], w_[3]} + vv * (f32x2){k_[2], k_[3]};
;                             S01 = sv * (f32x2){b_[0], b_[1]} + S01;
;                             S23 = sv * (f32x2){b_[2], b_[3]} + S23;
;                             rp = r_;
;                             a_ = a_n; w_ = w_n; b_ = b_n; k_ = k_n; r_ = r_n;
	v_pk_mul_f32 v[118:119], v[94:95], v[14:15] op_sel_hi:[0,1]
	v_add_f32_e32 v229, v116, v117
	v_add_f32_dpp v122, v122, v122 quad_perm:[1,0,3,2] row_mask:0xf bank_mask:0xf bound_ctrl:1
	v_pk_mul_f32 v[120:121], v[94:95], v[16:17] op_sel_hi:[0,1]
	v_add_f32_dpp v221, v221, v221 row_mirror row_mask:0xf bank_mask:0xf bound_ctrl:1
	v_add_f32_dpp v122, v122, v122 quad_perm:[2,3,0,1] row_mask:0xf bank_mask:0xf bound_ctrl:1
	v_pk_fma_f32 v[166:167], v[166:167], v[6:7], v[118:119]
	v_add_f32_dpp v221, v229, v229 row_mirror row_mask:0xf bank_mask:0xc bound_ctrl:1
	v_add_f32_dpp v122, v122, v122 row_half_mirror row_mask:0xf bank_mask:0xf bound_ctrl:1
	v_pk_fma_f32 v[164:165], v[164:165], v[8:9], v[120:121]
	s_nop 0
	v_add_f32_dpp v122, v122, v122 row_mirror row_mask:0xf bank_mask:0xf bound_ctrl:1
	s_nop 0
	v_pk_fma_f32 v[166:167], v[10:11], v[122:123], v[166:167] op_sel_hi:[1,0,1]
	v_pk_fma_f32 v[164:165], v[12:13], v[122:123], v[164:165] op_sel_hi:[1,0,1]
	s_waitcnt lgkmcnt(10)
	v_pk_mul_f32 v[114:115], v[166:167], v[22:23]
	v_pk_mul_f32 v[116:117], v[166:167], v[18:19]
	v_pk_fma_f32 v[114:115], v[164:165], v[24:25], v[114:115]
	v_pk_fma_f32 v[116:117], v[164:165], v[20:21], v[116:117]
	ds_read_b128 v[14:17], v124 offset:20480
	ds_read_b128 v[6:9], v124 offset:12288
	ds_read_b128 v[10:13], v124 offset:36864
	ds_read_b128 v[18:21], v124 offset:4096
	ds_read_b128 v[2:5], v124 offset:28672
	ds_read_b128 v[98:101], v125 offset:41024
	v_add_f32_e32 v122, v114, v115
	v_pk_mul_f32 v[118:119], v[94:95], v[34:35] op_sel:[1,0]
	v_add_f32_e32 v230, v116, v117
	v_add_f32_dpp v122, v122, v122 quad_perm:[1,0,3,2] row_mask:0xf bank_mask:0xf bound_ctrl:1
	v_pk_mul_f32 v[120:121], v[94:95], v[36:37] op_sel:[1,0]
	v_add_f32_dpp v222, v222, v222 row_mirror row_mask:0xf bank_mask:0xf bound_ctrl:1
	v_add_f32_dpp v122, v122, v122 quad_perm:[2,3,0,1] row_mask:0xf bank_mask:0xf bound_ctrl:1
	v_pk_fma_f32 v[166:167], v[166:167], v[26:27], v[118:119]
	v_add_f32_dpp v222, v230, v230 row_mirror row_mask:0xf bank_mask:0xc bound_ctrl:1
	v_add_f32_dpp v122, v122, v122 row_half_mirror row_mask:0xf bank_mask:0xf bound_ctrl:1
	v_pk_fma_f32 v[164:165], v[164:165], v[28:29], v[120:121]
	s_nop 0
	v_add_f32_dpp v122, v122, v122 row_mirror row_mask:0xf bank_mask:0xf bound_ctrl:1
	s_nop 0
	v_pk_fma_f32 v[166:167], v[30:31], v[122:123], v[166:167] op_sel_hi:[1,0,1]
	v_pk_fma_f32 v[164:165], v[32:33], v[122:123], v[164:165] op_sel_hi:[1,0,1]
	s_waitcnt lgkmcnt(11)
	v_pk_mul_f32 v[114:115], v[166:167], v[42:43]
	v_pk_mul_f32 v[116:117], v[166:167], v[38:39]
	v_pk_fma_f32 v[114:115], v[164:165], v[44:45], v[114:115]
	v_pk_fma_f32 v[116:117], v[164:165], v[40:41], v[116:117]
	ds_read_b128 v[34:37], v124 offset:20736
	ds_read_b128 v[26:29], v124 offset:12544
	ds_read_b128 v[30:33], v124 offset:37120
	ds_read_b128 v[38:41], v124 offset:4352
	ds_read_b128 v[22:25], v124 offset:28928
	v_add_f32_e32 v122, v114, v115
	v_pk_mul_f32 v[118:119], v[96:97], v[54:55] op_sel_hi:[0,1]
	v_add_f32_e32 v231, v116, v117
	v_add_f32_dpp v122, v122, v122 quad_perm:[1,0,3,2] row_mask:0xf bank_mask:0xf bound_ctrl:1
	v_pk_mul_f32 v[120:121], v[96:97], v[56:57] op_sel_hi:[0,1]
	v_add_f32_dpp v223, v223, v223 row_mirror row_mask:0xf bank_mask:0xf bound_ctrl:1
	v_add_f32_dpp v122, v122, v122 quad_perm:[2,3,0,1] row_mask:0xf bank_mask:0xf bound_ctrl:1
	v_pk_fma_f32 v[166:167], v[166:167], v[46:47], v[118:119]
	v_add_f32_dpp v223, v231, v231 row_mirror row_mask:0xf bank_mask:0xc bound_ctrl:1
	v_add_f32_dpp v122, v122, v122 row_half_mirror row_mask:0xf bank_mask:0xf bound_ctrl:1
	v_pk_fma_f32 v[164:165], v[164:165], v[48:49], v[120:121]
	s_nop 0
	v_add_f32_dpp v122, v122, v122 row_mirror row_mask:0xf bank_mask:0xf bound_ctrl:1
	s_nop 0
	v_pk_fma_f32 v[166:167], v[50:51], v[122:123], v[166:167] op_sel_hi:[1,0,1]
	v_pk_fma_f32 v[164:165], v[52:53], v[122:123], v[164:165] op_sel_hi:[1,0,1]
	s_waitcnt lgkmcnt(11)
	v_pk_mul_f32 v[114:115], v[166:167], v[62:63]
	v_pk_mul_f32 v[116:117], v[166:167], v[58:59]
	v_pk_fma_f32 v[114:115], v[164:165], v[64:65], v[114:115]
	v_pk_fma_f32 v[116:117], v[164:165], v[60:61], v[116:117]
	ds_read_b128 v[54:57], v124 offset:20992
	ds_read_b128 v[46:49], v124 offset:12800
	ds_read_b128 v[50:53], v124 offset:37376
	ds_read_b128 v[58:61], v124 offset:4608
	ds_read_b128 v[42:45], v124 offset:29184
	v_add_f32_e32 v122, v114, v115
	v_pk_mul_f32 v[118:119], v[96:97], v[74:75] op_sel:[1,0]
	v_add_f32_e32 v232, v116, v117
	v_add_f32_dpp v122, v122, v122 quad_perm:[1,0,3,2] row_mask:0xf bank_mask:0xf bound_ctrl:1
	v_pk_mul_f32 v[120:121], v[96:97], v[76:77] op_sel:[1,0]
	v_add_f32_dpp v224, v224, v224 row_mirror row_mask:0xf bank_mask:0xf bound_ctrl:1
	v_add_f32_dpp v122, v122, v122 quad_perm:[2,3,0,1] row_mask:0xf bank_mask:0xf bound_ctrl:1
	v_pk_fma_f32 v[166:167], v[166:167], v[66:67], v[118:119]
	v_add_f32_dpp v224, v232, v232 row_mirror row_mask:0xf bank_mask:0xc bound_ctrl:1
	v_add_f32_dpp v122, v122, v122 row_half_mirror row_mask:0xf bank_mask:0xf bound_ctrl:1
	v_pk_fma_f32 v[164:165], v[164:165], v[68:69], v[120:121]
	s_nop 0
	v_add_f32_dpp v122, v122, v122 row_mirror row_mask:0xf bank_mask:0xf bound_ctrl:1
	s_nop 0
	v_pk_fma_f32 v[166:167], v[70:71], v[122:123], v[166:167] op_sel_hi:[1,0,1]
	v_pk_fma_f32 v[164:165], v[72:73], v[122:123], v[164:165] op_sel_hi:[1,0,1]
	s_waitcnt lgkmcnt(11)
	v_pk_mul_f32 v[114:115], v[166:167], v[2:3]
	v_pk_mul_f32 v[116:117], v[166:167], v[78:79]
	v_pk_fma_f32 v[114:115], v[164:165], v[4:5], v[114:115]
	v_pk_fma_f32 v[116:117], v[164:165], v[80:81], v[116:117]
	ds_read_b128 v[74:77], v124 offset:21248
	ds_read_b128 v[66:69], v124 offset:13056
	ds_read_b128 v[70:73], v124 offset:37632
	ds_read_b128 v[78:81], v124 offset:4864
	ds_read_b128 v[62:65], v124 offset:29440
	v_add_f32_e32 v122, v114, v115
	s_waitcnt lgkmcnt(15)
; #define LAS __attribute__((address_space(3)))
; template <int CTRL> __device__ __forceinline__ float dpp_f(float x) { return __int_as_float(__builtin_amdgcn_update_dpp(0, __float_as_int(x), CTRL, 0xf, 0xf, false)); }
; __device__ __forceinline__ void phase_scan(const Params& p, LAS unsigned char* lds) {
;     ...
;                         for (int u16 = 0; u16 < 16; ++u16) {
;                             const int s = 16 * hb + u16;
;                             const int sn = (s + 1) & 31;
;                             const f32x4 a_n = *(const LAS f32x4*)(sA + sn * 64), w_n = *(const LAS f32x4*)(sW + sn * 64), b_n = *(const LAS f32x4*)(sB + sn * 64);
;                             const f32x4 k_n = *(const LAS f32x4*)(sK + sn * 64), r_n = *(const LAS f32x4*)(sR + sn * 64);
;                             const float v = vq[u16 >> 2][u16 & 3];
;                             const f32x2 vv = {v, v};
;                             f32x2 pp = S01 * (f32x2){a_[0], a_[1]}; pp = S23 * (f32x2){a_[2], a_[3]} + pp;
;                             f32x2 yy = S01 * (f32x2){rp[0], rp[1]}; yy = S23 * (f32x2){rp[2], rp[3]} + yy;
;                             float sa = pp[0] + pp[1], y = yy[0] + yy[1];
;                             sa += dpp_f<0xB1>(sa); y += dpp_f<0xB1>(y);
;                             sa += dpp_f<0x4E>(sa); y += dpp_f<0x4E>(y);
;                             sa += dpp_f<0x141>(sa); y += dpp_f<0x141>(y);
;                             sa += dpp_f<0x140>(sa); y += dpp_f<0x140>(y);
;                             sY[((s - 1) & 31) * 16 + srow] = y;
;                             const f32x2 sv = {sa, sa};
;                             S01 = S01 * (f32x2){w_[0], w_[1]} + vv * (f32x2){k_[0], k_[1]};
;                             S23 = S23 * (f32x2){w_[2], w_[3]} + vv * (f32x2){k_[2], k_[3]};
;                             S01 = sv * (f32x2){b_[0], b_[1]} + S01;
;                             S23 = sv * (f32x2){b_[2], b_[3]} + S23;
;                             rp = r_;
;                             a_ = a_n; w_ = w_n; b_ = b_n; k_ = k_n; r_ = r_n;
;                         }
	v_pk_mul_f32 v[118:119], v[98:99], v[14:15] op_sel_hi:[0,1]
	v_add_f32_e32 v233, v116, v117
	v_add_f32_dpp v122, v122, v122 quad_perm:[1,0,3,2] row_mask:0xf bank_mask:0xf bound_ctrl:1
	v_pk_mul_f32 v[120:121], v[98:99], v[16:17] op_sel_hi:[0,1]
	v_add_f32_dpp v225, v225, v225 row_mirror row_mask:0xf bank_mask:0xf bound_ctrl:1
	v_add_f32_dpp v122, v122, v122 quad_perm:[2,3,0,1] row_mask:0xf bank_mask:0xf bound_ctrl:1
	v_pk_fma_f32 v[166:167], v[166:167], v[6:7], v[118:119]
	v_add_f32_dpp v225, v233, v233 row_mirror row_mask:0xf bank_mask:0xc bound_ctrl:1
	v_add_f32_dpp v122, v122, v122 row_half_mirror row_mask:0xf bank_mask:0xf bound_ctrl:1
	v_pk_fma_f32 v[164:165], v[164:165], v[8:9], v[120:121]
	s_nop 0
	v_add_f32_dpp v122, v122, v122 row_mirror row_mask:0xf bank_mask:0xf bound_ctrl:1
	s_nop 0
	v_pk_fma_f32 v[166:167], v[10:11], v[122:123], v[166:167] op_sel_hi:[1,0,1]
	v_pk_fma_f32 v[164:165], v[12:13], v[122:123], v[164:165] op_sel_hi:[1,0,1]
	s_waitcnt lgkmcnt(10)
	v_pk_mul_f32 v[114:115], v[166:167], v[22:23]
	v_pk_mul_f32 v[116:117], v[166:167], v[18:19]
	v_pk_fma_f32 v[114:115], v[164:165], v[24:25], v[114:115]
	v_pk_fma_f32 v[116:117], v[164:165], v[20:21], v[116:117]
	ds_read_b128 v[14:17], v124 offset:21504
	ds_read_b128 v[6:9], v124 offset:13312
	ds_read_b128 v[10:13], v124 offset:37888
	ds_read_b128 v[18:21], v124 offset:5120
	ds_read_b128 v[2:5], v124 offset:29696
	ds_read_b128 v[102:105], v125 offset:41040
	v_add_f32_e32 v122, v114, v115
	v_pk_mul_f32 v[118:119], v[98:99], v[34:35] op_sel:[1,0]
	v_add_f32_e32 v234, v116, v117
	v_add_f32_dpp v122, v122, v122 quad_perm:[1,0,3,2] row_mask:0xf bank_mask:0xf bound_ctrl:1
	v_pk_mul_f32 v[120:121], v[98:99], v[36:37] op_sel:[1,0]
	v_add_f32_dpp v226, v226, v226 row_mirror row_mask:0xf bank_mask:0xf bound_ctrl:1
	v_add_f32_dpp v122, v122, v122 quad_perm:[2,3,0,1] row_mask:0xf bank_mask:0xf bound_ctrl:1
	v_pk_fma_f32 v[166:167], v[166:167], v[26:27], v[118:119]
	v_add_f32_dpp v226, v234, v234 row_mirror row_mask:0xf bank_mask:0xc bound_ctrl:1
	v_add_f32_dpp v122, v122, v122 row_half_mirror row_mask:0xf bank_mask:0xf bound_ctrl:1
	v_pk_fma_f32 v[164:165], v[164:165], v[28:29], v[120:121]
	s_nop 0
	v_add_f32_dpp v122, v122, v122 row_mirror row_mask:0xf bank_mask:0xf bound_ctrl:1
	s_nop 0
	v_pk_fma_f32 v[166:167], v[30:31], v[122:123], v[166:167] op_sel_hi:[1,0,1]
	v_pk_fma_f32 v[164:165], v[32:33], v[122:123], v[164:165] op_sel_hi:[1,0,1]
	s_waitcnt lgkmcnt(11)
	v_pk_mul_f32 v[114:115], v[166:167], v[42:43]
	v_pk_mul_f32 v[116:117], v[166:167], v[38:39]
	v_pk_fma_f32 v[114:115], v[164:165], v[44:45], v[114:115]
	v_pk_fma_f32 v[116:117], v[164:165], v[40:41], v[116:117]
	ds_read_b128 v[34:37], v124 offset:21760
	ds_read_b128 v[26:29], v124 offset:13568
	ds_read_b128 v[30:33], v124 offset:38144
	ds_read_b128 v[38:41], v124 offset:5376
	ds_read_b128 v[22:25], v124 offset:29952
	v_add_f32_e32 v122, v114, v115
	v_pk_mul_f32 v[118:119], v[100:101], v[54:55] op_sel_hi:[0,1]
	v_add_f32_e32 v235, v116, v117
	v_add_f32_dpp v122, v122, v122 quad_perm:[1,0,3,2] row_mask:0xf bank_mask:0xf bound_ctrl:1
	v_pk_mul_f32 v[120:121], v[100:101], v[56:57] op_sel_hi:[0,1]
	v_add_f32_dpp v227, v227, v227 row_mirror row_mask:0xf bank_mask:0xf bound_ctrl:1
	v_add_f32_dpp v122, v122, v122 quad_perm:[2,3,0,1] row_mask:0xf bank_mask:0xf bound_ctrl:1
	v_pk_fma_f32 v[166:167], v[166:167], v[46:47], v[118:119]
	v_add_f32_dpp v227, v235, v235 row_mirror row_mask:0xf bank_mask:0xc bound_ctrl:1
	v_add_f32_dpp v122, v122, v122 row_half_mirror row_mask:0xf bank_mask:0xf bound_ctrl:1
	v_pk_fma_f32 v[164:165], v[164:165], v[48:49], v[120:121]
	v_add_f32_dpp v220, v220, v220 row_half_mirror row_mask:0xf bank_mask:0xf bound_ctrl:1
	v_add_f32_dpp v122, v122, v122 row_mirror row_mask:0xf bank_mask:0xf bound_ctrl:1
	v_add_f32_dpp v221, v221, v221 row_half_mirror row_mask:0xf bank_mask:0xf bound_ctrl:1
	v_add_f32_dpp v222, v222, v222 row_half_mirror row_mask:0xf bank_mask:0xf bound_ctrl:1
	v_pk_fma_f32 v[166:167], v[50:51], v[122:123], v[166:167] op_sel_hi:[1,0,1]
	v_pk_fma_f32 v[164:165], v[52:53], v[122:123], v[164:165] op_sel_hi:[1,0,1]
	v_add_f32_dpp v223, v223, v223 row_half_mirror row_mask:0xf bank_mask:0xf bound_ctrl:1
	v_add_f32_dpp v220, v224, v224 row_half_mirror row_mask:0xf bank_mask:0xa bound_ctrl:1
	s_waitcnt lgkmcnt(11)
	v_pk_mul_f32 v[114:115], v[166:167], v[62:63]
	v_pk_mul_f32 v[116:117], v[166:167], v[58:59]
	v_pk_fma_f32 v[114:115], v[164:165], v[64:65], v[114:115]
	v_pk_fma_f32 v[116:117], v[164:165], v[60:61], v[116:117]
	ds_read_b128 v[54:57], v124 offset:22016
	ds_read_b128 v[46:49], v124 offset:13824
	ds_read_b128 v[50:53], v124 offset:38400
	ds_read_b128 v[58:61], v124 offset:5632
	ds_read_b128 v[42:45], v124 offset:30208
	v_add_f32_e32 v122, v114, v115
	v_pk_mul_f32 v[118:119], v[100:101], v[74:75] op_sel:[1,0]
	v_add_f32_e32 v204, v116, v117
	v_add_f32_dpp v122, v122, v122 quad_perm:[1,0,3,2] row_mask:0xf bank_mask:0xf bound_ctrl:1
	v_pk_mul_f32 v[120:121], v[100:101], v[76:77] op_sel:[1,0]
	v_add_f32_dpp v221, v225, v225 row_half_mirror row_mask:0xf bank_mask:0xa bound_ctrl:1
	v_add_f32_dpp v122, v122, v122 quad_perm:[2,3,0,1] row_mask:0xf bank_mask:0xf bound_ctrl:1
	v_pk_fma_f32 v[166:167], v[166:167], v[66:67], v[118:119]
	v_add_f32_dpp v222, v226, v226 row_half_mirror row_mask:0xf bank_mask:0xa bound_ctrl:1
	v_add_f32_dpp v122, v122, v122 row_half_mirror row_mask:0xf bank_mask:0xf bound_ctrl:1
	v_pk_fma_f32 v[164:165], v[164:165], v[68:69], v[120:121]
	v_add_f32_dpp v223, v227, v227 row_half_mirror row_mask:0xf bank_mask:0xa bound_ctrl:1
	v_add_f32_dpp v122, v122, v122 row_mirror row_mask:0xf bank_mask:0xf bound_ctrl:1
	v_add_f32_dpp v220, v220, v220 quad_perm:[1,0,3,2] row_mask:0xf bank_mask:0xf bound_ctrl:1
	v_add_f32_dpp v221, v221, v221 quad_perm:[1,0,3,2] row_mask:0xf bank_mask:0xf bound_ctrl:1
	v_pk_fma_f32 v[166:167], v[70:71], v[122:123], v[166:167] op_sel_hi:[1,0,1]
	v_pk_fma_f32 v[164:165], v[72:73], v[122:123], v[164:165] op_sel_hi:[1,0,1]
	v_add_f32_dpp v222, v222, v222 quad_perm:[1,0,3,2] row_mask:0xf bank_mask:0xf bound_ctrl:1
	v_add_f32_dpp v223, v223, v223 quad_perm:[1,0,3,2] row_mask:0xf bank_mask:0xf bound_ctrl:1
	s_waitcnt lgkmcnt(11)
; #define LAS __attribute__((address_space(3)))
; template <int CTRL> __device__ __forceinline__ float dpp_f(float x) { return __int_as_float(__builtin_amdgcn_update_dpp(0, __float_as_int(x), CTRL, 0xf, 0xf, false)); }
; __device__ __forceinline__ void phase_scan(const Params& p, LAS unsigned char* lds) {
;     ...
;                         for (int u16 = 0; u16 < 16; ++u16) {
;                             const int s = 16 * hb + u16;
;                             const int sn = (s + 1) & 31;
;                             const f32x4 a_n = *(const LAS f32x4*)(sA + sn * 64), w_n = *(const LAS f32x4*)(sW + sn * 64), b_n = *(const LAS f32x4*)(sB + sn * 64);
;                             const f32x4 k_n = *(const LAS f32x4*)(sK + sn * 64), r_n = *(const LAS f32x4*)(sR + sn * 64);
;                             const float v = vq[u16 >> 2][u16 & 3];
;                             const f32x2 vv = {v, v};
;                             f32x2 pp = S01 * (f32x2){a_[0], a_[1]}; pp = S23 * (f32x2){a_[2], a_[3]} + pp;
;                             f32x2 yy = S01 * (f32x2){rp[0], rp[1]}; yy = S23 * (f32x2){rp[2], rp[3]} + yy;
;                             float sa = pp[0] + pp[1], y = yy[0] + yy[1];
;                             sa += dpp_f<0xB1>(sa); y += dpp_f<0xB1>(y);
;                             sa += dpp_f<0x4E>(sa); y += dpp_f<0x4E>(y);
;                             sa += dpp_f<0x141>(sa); y += dpp_f<0x141>(y);
;                             sa += dpp_f<0x140>(sa); y += dpp_f<0x140>(y);
;                             sY[((s - 1) & 31) * 16 + srow] = y;
;                             const f32x2 sv = {sa, sa};
;                             S01 = S01 * (f32x2){w_[0], w_[1]} + vv * (f32x2){k_[0], k_[1]};
;                             S23 = S23 * (f32x2){w_[2], w_[3]} + vv * (f32x2){k_[2], k_[3]};
;                             S01 = sv * (f32x2){b_[0], b_[1]} + S01;
;                             S23 = sv * (f32x2){b_[2], b_[3]} + S23;
;                             rp = r_;
;                             a_ = a_n; w_ = w_n; b_ = b_n; k_ = k_n; r_ = r_n;
;                         }
	v_pk_mul_f32 v[114:115], v[166:167], v[2:3]
	v_pk_mul_f32 v[116:117], v[166:167], v[78:79]
	v_pk_fma_f32 v[114:115], v[164:165], v[4:5], v[114:115]
	v_pk_fma_f32 v[116:117], v[164:165], v[80:81], v[116:117]
	ds_read_b128 v[74:77], v124 offset:22272
	ds_read_b128 v[66:69], v124 offset:14080
	ds_read_b128 v[70:73], v124 offset:38656
	ds_read_b128 v[78:81], v124 offset:5888
	ds_read_b128 v[62:65], v124 offset:30464
	v_add_f32_e32 v122, v114, v115
	s_waitcnt lgkmcnt(15)
	v_pk_mul_f32 v[118:119], v[102:103], v[14:15] op_sel_hi:[0,1]
	v_add_f32_e32 v205, v116, v117
	v_add_f32_dpp v122, v122, v122 quad_perm:[1,0,3,2] row_mask:0xf bank_mask:0xf bound_ctrl:1
	v_pk_mul_f32 v[120:121], v[102:103], v[16:17] op_sel_hi:[0,1]
	v_add_f32_dpp v220, v220, v220 quad_perm:[2,3,0,1] row_mask:0xf bank_mask:0xf bound_ctrl:1
	v_add_f32_dpp v122, v122, v122 quad_perm:[2,3,0,1] row_mask:0xf bank_mask:0xf bound_ctrl:1
	v_pk_fma_f32 v[166:167], v[166:167], v[6:7], v[118:119]
	v_add_f32_dpp v221, v221, v221 quad_perm:[2,3,0,1] row_mask:0xf bank_mask:0xf bound_ctrl:1
	v_add_f32_dpp v122, v122, v122 row_half_mirror row_mask:0xf bank_mask:0xf bound_ctrl:1
	v_pk_fma_f32 v[164:165], v[164:165], v[8:9], v[120:121]
	v_add_f32_dpp v222, v222, v222 quad_perm:[2,3,0,1] row_mask:0xf bank_mask:0xf bound_ctrl:1
	v_add_f32_dpp v122, v122, v122 row_mirror row_mask:0xf bank_mask:0xf bound_ctrl:1
	v_add_f32_dpp v223, v223, v223 quad_perm:[2,3,0,1] row_mask:0xf bank_mask:0xf bound_ctrl:1
	v_cndmask_b32_e64 v202, v220, v221, s[34:35]
	v_pk_fma_f32 v[166:167], v[10:11], v[122:123], v[166:167] op_sel_hi:[1,0,1]
	v_pk_fma_f32 v[164:165], v[12:13], v[122:123], v[164:165] op_sel_hi:[1,0,1]
	v_cndmask_b32_e64 v202, v202, v222, s[56:57]
	v_cndmask_b32_e64 v202, v202, v223, s[98:99]
	s_waitcnt lgkmcnt(10)
	v_pk_mul_f32 v[114:115], v[166:167], v[22:23]
	v_pk_mul_f32 v[116:117], v[166:167], v[18:19]
	v_pk_fma_f32 v[114:115], v[164:165], v[24:25], v[114:115]
	v_pk_fma_f32 v[116:117], v[164:165], v[20:21], v[116:117]
	ds_read_b128 v[14:17], v124 offset:22528
	ds_read_b128 v[6:9], v124 offset:14336
	ds_read_b128 v[10:13], v124 offset:38912
	ds_read_b128 v[18:21], v124 offset:6144
	ds_read_b128 v[2:5], v124 offset:30720
	ds_read_b128 v[106:109], v125 offset:41056
	v_add_f32_e32 v122, v114, v115
	v_pk_mul_f32 v[118:119], v[102:103], v[34:35] op_sel:[1,0]
	v_add_f32_e32 v206, v116, v117
	v_add_f32_dpp v122, v122, v122 quad_perm:[1,0,3,2] row_mask:0xf bank_mask:0xf bound_ctrl:1
	v_pk_mul_f32 v[120:121], v[102:103], v[36:37] op_sel:[1,0]
	v_cvt_f16_f32_e32 v203, v202
	v_add_f32_dpp v122, v122, v122 quad_perm:[2,3,0,1] row_mask:0xf bank_mask:0xf bound_ctrl:1
	v_pk_fma_f32 v[166:167], v[166:167], v[26:27], v[118:119]
	global_store_short v[126:127], v203, off
	v_add_f32_dpp v122, v122, v122 row_half_mirror row_mask:0xf bank_mask:0xf bound_ctrl:1
	v_pk_fma_f32 v[164:165], v[164:165], v[28:29], v[120:121]
	v_lshl_add_u64 v[126:127], v[126:127], 0, s[100:101]
	v_add_f32_dpp v122, v122, v122 row_mirror row_mask:0xf bank_mask:0xf bound_ctrl:1
	s_nop 0
	v_pk_fma_f32 v[166:167], v[30:31], v[122:123], v[166:167] op_sel_hi:[1,0,1]
	v_pk_fma_f32 v[164:165], v[32:33], v[122:123], v[164:165] op_sel_hi:[1,0,1]
	s_waitcnt lgkmcnt(11)
	v_pk_mul_f32 v[114:115], v[166:167], v[42:43]
	v_pk_mul_f32 v[116:117], v[166:167], v[38:39]
	v_pk_fma_f32 v[114:115], v[164:165], v[44:45], v[114:115]
	v_pk_fma_f32 v[116:117], v[164:165], v[40:41], v[116:117]
	ds_read_b128 v[34:37], v124 offset:22784
	ds_read_b128 v[26:29], v124 offset:14592
	ds_read_b128 v[30:33], v124 offset:39168
	ds_read_b128 v[38:41], v124 offset:6400
	ds_read_b128 v[22:25], v124 offset:30976
	v_add_f32_e32 v122, v114, v115
	v_pk_mul_f32 v[118:119], v[104:105], v[54:55] op_sel_hi:[0,1]
	v_add_f32_e32 v207, v116, v117
	v_add_f32_dpp v122, v122, v122 quad_perm:[1,0,3,2] row_mask:0xf bank_mask:0xf bound_ctrl:1
	v_pk_mul_f32 v[120:121], v[104:105], v[56:57] op_sel_hi:[0,1]
	s_nop 0
	v_add_f32_dpp v122, v122, v122 quad_perm:[2,3,0,1] row_mask:0xf bank_mask:0xf bound_ctrl:1
	v_pk_fma_f32 v[166:167], v[166:167], v[46:47], v[118:119]
	s_nop 0
	v_add_f32_dpp v122, v122, v122 row_half_mirror row_mask:0xf bank_mask:0xf bound_ctrl:1
	v_pk_fma_f32 v[164:165], v[164:165], v[48:49], v[120:121]
	s_nop 0
	v_add_f32_dpp v122, v122, v122 row_mirror row_mask:0xf bank_mask:0xf bound_ctrl:1
	s_nop 0
	v_pk_fma_f32 v[166:167], v[50:51], v[122:123], v[166:167] op_sel_hi:[1,0,1]
	v_pk_fma_f32 v[164:165], v[52:53], v[122:123], v[164:165] op_sel_hi:[1,0,1]
	s_waitcnt lgkmcnt(11)
	v_pk_mul_f32 v[114:115], v[166:167], v[62:63]
	v_pk_mul_f32 v[116:117], v[166:167], v[58:59]
	v_pk_fma_f32 v[114:115], v[164:165], v[64:65], v[114:115]
	v_pk_fma_f32 v[116:117], v[164:165], v[60:61], v[116:117]
	ds_read_b128 v[54:57], v124 offset:23040
	ds_read_b128 v[46:49], v124 offset:14848
	ds_read_b128 v[50:53], v124 offset:39424
	ds_read_b128 v[58:61], v124 offset:6656
	ds_read_b128 v[42:45], v124 offset:31232
	v_add_f32_e32 v122, v114, v115
	v_pk_mul_f32 v[118:119], v[104:105], v[74:75] op_sel:[1,0]
	v_add_f32_e32 v208, v116, v117
	v_add_f32_dpp v122, v122, v122 quad_perm:[1,0,3,2] row_mask:0xf bank_mask:0xf bound_ctrl:1
	v_pk_mul_f32 v[120:121], v[104:105], v[76:77] op_sel:[1,0]
	s_nop 0
	v_add_f32_dpp v122, v122, v122 quad_perm:[2,3,0,1] row_mask:0xf bank_mask:0xf bound_ctrl:1
	v_pk_fma_f32 v[166:167], v[166:167], v[66:67], v[118:119]
	s_nop 0
	v_add_f32_dpp v122, v122, v122 row_half_mirror row_mask:0xf bank_mask:0xf bound_ctrl:1
	v_pk_fma_f32 v[164:165], v[164:165], v[68:69], v[120:121]
	s_nop 0
	v_add_f32_dpp v122, v122, v122 row_mirror row_mask:0xf bank_mask:0xf bound_ctrl:1
	s_nop 0
	v_pk_fma_f32 v[166:167], v[70:71], v[122:123], v[166:167] op_sel_hi:[1,0,1]
	v_pk_fma_f32 v[164:165], v[72:73], v[122:123], v[164:165] op_sel_hi:[1,0,1]
	s_waitcnt lgkmcnt(11)
; #define LAS __attribute__((address_space(3)))
; __device__ __forceinline__ void phase_scan(const Params& p, LAS unsigned char* lds) {
;     ...
;                         for (int u16 = 0; u16 < 16; ++u16) {
;                             const int s = 16 * hb + u16;
;                             const int sn = (s + 1) & 31;
;                             const f32x4 a_n = *(const LAS f32x4*)(sA + sn * 64), w_n = *(const LAS f32x4*)(sW + sn * 64), b_n = *(const LAS f32x4*)(sB + sn * 64);
;                             const f32x4 k_n = *(const LAS f32x4*)(sK + sn * 64), r_n = *(const LAS f32x4*)(sR + sn * 64);
;                             const float v = vq[u16 >> 2][u16 & 3];
;                             const f32x2 vv = {v, v};
;                             f32x2 pp = S01 * (f32x2){a_[0], a_[1]}; pp = S23 * (f32x2){a_[2], a_[3]} + pp;
;                             f32x2 yy = S01 * (f32x2){rp[0], rp[1]}; yy = S23 * (f32x2){rp[2], rp[3]} + yy;
;                             float sa = pp[0] + pp[1], y = yy[0] + yy[1];
;                             sa += dpp_f<0xB1>(sa); y += dpp_f<0xB1>(y);
;                             sa += dpp_f<0x4E>(sa); y += dpp_f<0x4E>(y);
;                             sa += dpp_f<0x141>(sa); y += dpp_f<0x141>(y);
;                             sa += dpp_f<0x140>(sa); y += dpp_f<0x140>(y);
;                             sY[((s - 1) & 31) * 16 + srow] = y;
;                             const f32x2 sv = {sa, sa};
;                             S01 = S01 * (f32x2){w_[0], w_[1]} + vv * (f32x2){k_[0], k_[1]};
;                             S23 = S23 * (f32x2){w_[2], w_[3]} + vv * (f32x2){k_[2], k_[3]};
;                             S01 = sv * (f32x2){b_[0], b_[1]} + S01;
;                             S23 = sv * (f32x2){b_[2], b_[3]} + S23;
;                             rp = r_;
;                             a_ = a_n; w_ = w_n; b_ = b_n; k_ = k_n; r_ = r_n;
;                         }
; #pragma unroll
;                         for (int u = 0; u < 4; ++u) vq[u] = vn[u];
;                     }
;                     { f32x2 yy = S01 * (f32x2){rp[0], rp[1]}; yy = S23 * (f32x2){rp[2], rp[3]} + yy; sY[31 * 16 + srow] = red16(yy[0] + yy[1]); }
;                     __builtin_amdgcn_s_setprio(0);
	v_pk_mul_f32 v[114:115], v[166:167], v[2:3]
	v_pk_mul_f32 v[116:117], v[166:167], v[78:79]
	v_pk_fma_f32 v[114:115], v[164:165], v[4:5], v[114:115]
	v_pk_fma_f32 v[116:117], v[164:165], v[80:81], v[116:117]
	ds_read_b128 v[74:77], v124 offset:23296
	ds_read_b128 v[66:69], v124 offset:15104
	ds_read_b128 v[70:73], v124 offset:39680
	ds_read_b128 v[78:81], v124 offset:6912
	ds_read_b128 v[62:65], v124 offset:31488
	v_add_f32_e32 v122, v114, v115
	s_waitcnt lgkmcnt(15)
	v_pk_mul_f32 v[118:119], v[106:107], v[14:15] op_sel_hi:[0,1]
	v_add_f32_e32 v209, v116, v117
	v_add_f32_dpp v122, v122, v122 quad_perm:[1,0,3,2] row_mask:0xf bank_mask:0xf bound_ctrl:1
	v_pk_mul_f32 v[120:121], v[106:107], v[16:17] op_sel_hi:[0,1]
	s_nop 0
	v_add_f32_dpp v122, v122, v122 quad_perm:[2,3,0,1] row_mask:0xf bank_mask:0xf bound_ctrl:1
	v_pk_fma_f32 v[166:167], v[166:167], v[6:7], v[118:119]
	s_nop 0
	v_add_f32_dpp v122, v122, v122 row_half_mirror row_mask:0xf bank_mask:0xf bound_ctrl:1
	v_pk_fma_f32 v[164:165], v[164:165], v[8:9], v[120:121]
	s_nop 0
	v_add_f32_dpp v122, v122, v122 row_mirror row_mask:0xf bank_mask:0xf bound_ctrl:1
	s_nop 0
	v_pk_fma_f32 v[166:167], v[10:11], v[122:123], v[166:167] op_sel_hi:[1,0,1]
	v_pk_fma_f32 v[164:165], v[12:13], v[122:123], v[164:165] op_sel_hi:[1,0,1]
	s_waitcnt lgkmcnt(10)
	v_pk_mul_f32 v[114:115], v[166:167], v[22:23]
	v_pk_mul_f32 v[116:117], v[166:167], v[18:19]
	v_pk_fma_f32 v[114:115], v[164:165], v[24:25], v[114:115]
	v_pk_fma_f32 v[116:117], v[164:165], v[20:21], v[116:117]
	ds_read_b128 v[14:17], v124 offset:23552
	ds_read_b128 v[6:9], v124 offset:15360
	ds_read_b128 v[10:13], v124 offset:39936
	ds_read_b128 v[18:21], v124 offset:7168
	ds_read_b128 v[2:5], v124 offset:31744
	ds_read_b128 v[110:113], v125 offset:41072
	v_add_f32_e32 v122, v114, v115
	v_pk_mul_f32 v[118:119], v[106:107], v[34:35] op_sel:[1,0]
	v_add_f32_e32 v210, v116, v117
	v_add_f32_dpp v122, v122, v122 quad_perm:[1,0,3,2] row_mask:0xf bank_mask:0xf bound_ctrl:1
	v_pk_mul_f32 v[120:121], v[106:107], v[36:37] op_sel:[1,0]
	s_nop 0
	v_add_f32_dpp v122, v122, v122 quad_perm:[2,3,0,1] row_mask:0xf bank_mask:0xf bound_ctrl:1
	v_pk_fma_f32 v[166:167], v[166:167], v[26:27], v[118:119]
	s_nop 0
	v_add_f32_dpp v122, v122, v122 row_half_mirror row_mask:0xf bank_mask:0xf bound_ctrl:1
	v_pk_fma_f32 v[164:165], v[164:165], v[28:29], v[120:121]
	s_nop 0
	v_add_f32_dpp v122, v122, v122 row_mirror row_mask:0xf bank_mask:0xf bound_ctrl:1
	s_nop 0
	v_pk_fma_f32 v[166:167], v[30:31], v[122:123], v[166:167] op_sel_hi:[1,0,1]
	v_pk_fma_f32 v[164:165], v[32:33], v[122:123], v[164:165] op_sel_hi:[1,0,1]
	s_waitcnt lgkmcnt(11)
	v_pk_mul_f32 v[114:115], v[166:167], v[42:43]
	v_pk_mul_f32 v[116:117], v[166:167], v[38:39]
	v_pk_fma_f32 v[114:115], v[164:165], v[44:45], v[114:115]
	v_pk_fma_f32 v[116:117], v[164:165], v[40:41], v[116:117]
	ds_read_b128 v[34:37], v124 offset:23808
	ds_read_b128 v[26:29], v124 offset:15616
	ds_read_b128 v[30:33], v124 offset:40192
	ds_read_b128 v[38:41], v124 offset:7424
	ds_read_b128 v[22:25], v124 offset:32000
	v_add_f32_e32 v122, v114, v115
	v_pk_mul_f32 v[118:119], v[108:109], v[54:55] op_sel_hi:[0,1]
	v_add_f32_e32 v211, v116, v117
	v_add_f32_dpp v122, v122, v122 quad_perm:[1,0,3,2] row_mask:0xf bank_mask:0xf bound_ctrl:1
	v_pk_mul_f32 v[120:121], v[108:109], v[56:57] op_sel_hi:[0,1]
	s_nop 0
	v_add_f32_dpp v122, v122, v122 quad_perm:[2,3,0,1] row_mask:0xf bank_mask:0xf bound_ctrl:1
	v_pk_fma_f32 v[166:167], v[166:167], v[46:47], v[118:119]
	s_nop 0
	v_add_f32_dpp v122, v122, v122 row_half_mirror row_mask:0xf bank_mask:0xf bound_ctrl:1
	v_pk_fma_f32 v[164:165], v[164:165], v[48:49], v[120:121]
	s_nop 0
	v_add_f32_dpp v122, v122, v122 row_mirror row_mask:0xf bank_mask:0xf bound_ctrl:1
	s_nop 0
	v_pk_fma_f32 v[166:167], v[50:51], v[122:123], v[166:167] op_sel_hi:[1,0,1]
	v_pk_fma_f32 v[164:165], v[52:53], v[122:123], v[164:165] op_sel_hi:[1,0,1]
	s_waitcnt lgkmcnt(11)
	v_pk_mul_f32 v[114:115], v[166:167], v[62:63]
	v_pk_mul_f32 v[116:117], v[166:167], v[58:59]
	v_pk_fma_f32 v[114:115], v[164:165], v[64:65], v[114:115]
	v_pk_fma_f32 v[116:117], v[164:165], v[60:61], v[116:117]
	ds_read_b128 v[54:57], v124 offset:24064
	ds_read_b128 v[46:49], v124 offset:15872
	ds_read_b128 v[50:53], v124 offset:40448
	ds_read_b128 v[58:61], v124 offset:7680
	ds_read_b128 v[42:45], v124 offset:32256
	v_add_f32_e32 v122, v114, v115
	v_pk_mul_f32 v[118:119], v[108:109], v[74:75] op_sel:[1,0]
	v_add_f32_e32 v212, v116, v117
	v_add_f32_dpp v122, v122, v122 quad_perm:[1,0,3,2] row_mask:0xf bank_mask:0xf bound_ctrl:1
	v_pk_mul_f32 v[120:121], v[108:109], v[76:77] op_sel:[1,0]
	s_nop 0
	v_add_f32_dpp v122, v122, v122 quad_perm:[2,3,0,1] row_mask:0xf bank_mask:0xf bound_ctrl:1
	v_pk_fma_f32 v[166:167], v[166:167], v[66:67], v[118:119]
	s_nop 0
	v_add_f32_dpp v122, v122, v122 row_half_mirror row_mask:0xf bank_mask:0xf bound_ctrl:1
	v_pk_fma_f32 v[164:165], v[164:165], v[68:69], v[120:121]
	s_nop 0
	v_add_f32_dpp v122, v122, v122 row_mirror row_mask:0xf bank_mask:0xf bound_ctrl:1
	s_nop 0
	v_pk_fma_f32 v[166:167], v[70:71], v[122:123], v[166:167] op_sel_hi:[1,0,1]
	v_pk_fma_f32 v[164:165], v[72:73], v[122:123], v[164:165] op_sel_hi:[1,0,1]
	s_waitcnt lgkmcnt(11)
	v_pk_mul_f32 v[114:115], v[166:167], v[2:3]
	v_pk_mul_f32 v[116:117], v[166:167], v[78:79]
	v_pk_fma_f32 v[114:115], v[164:165], v[4:5], v[114:115]
	v_pk_fma_f32 v[116:117], v[164:165], v[80:81], v[116:117]
	ds_read_b128 v[74:77], v124 offset:24320
	ds_read_b128 v[66:69], v124 offset:16128
	ds_read_b128 v[70:73], v124 offset:40704
	ds_read_b128 v[78:81], v124 offset:7936
	ds_read_b128 v[62:65], v124 offset:32512
	v_add_f32_e32 v122, v114, v115
	s_waitcnt lgkmcnt(15)
	v_pk_mul_f32 v[118:119], v[110:111], v[14:15] op_sel_hi:[0,1]
	v_add_f32_e32 v213, v116, v117
	v_add_f32_dpp v122, v122, v122 quad_perm:[1,0,3,2] row_mask:0xf bank_mask:0xf bound_ctrl:1
	v_pk_mul_f32 v[120:121], v[110:111], v[16:17] op_sel_hi:[0,1]
	s_nop 0
	v_add_f32_dpp v122, v122, v122 quad_perm:[2,3,0,1] row_mask:0xf bank_mask:0xf bound_ctrl:1
	v_pk_fma_f32 v[166:167], v[166:167], v[6:7], v[118:119]
	s_nop 0
	v_add_f32_dpp v122, v122, v122 row_half_mirror row_mask:0xf bank_mask:0xf bound_ctrl:1
	v_pk_fma_f32 v[164:165], v[164:165], v[8:9], v[120:121]
	s_nop 0
	v_add_f32_dpp v122, v122, v122 row_mirror row_mask:0xf bank_mask:0xf bound_ctrl:1
	s_nop 0
	v_pk_fma_f32 v[166:167], v[10:11], v[122:123], v[166:167] op_sel_hi:[1,0,1]
	v_pk_fma_f32 v[164:165], v[12:13], v[122:123], v[164:165] op_sel_hi:[1,0,1]
	s_setprio 0
	s_branch .LBB0_603
; #define LAS __attribute__((address_space(3)))
; __device__ __forceinline__ void phase_scan(const Params& p, LAS unsigned char* lds) {
;     ...
;                         for (int u16 = 0; u16 < 16; ++u16) {
;                             const int s = 16 * hb + u16;
;                             const int sn = (s + 1) & 31;
;                             const f32x4 a_n = *(const LAS f32x4*)(sA + sn * 64), w_n = *(const LAS f32x4*)(sW + sn * 64), b_n = *(const LAS f32x4*)(sB + sn * 64);
;                             const f32x4 k_n = *(const LAS f32x4*)(sK + sn * 64), r_n = *(const LAS f32x4*)(sR + sn * 64);
;                             const float v = vq[u16 >> 2][u16 & 3];
;                             const f32x2 vv = {v, v};
;                             f32x2 pp = S01 * (f32x2){a_[0], a_[1]}; pp = S23 * (f32x2){a_[2], a_[3]} + pp;
;                             f32x2 yy = S01 * (f32x2){rp[0], rp[1]}; yy = S23 * (f32x2){rp[2], rp[3]} + yy;
;                             float sa = pp[0] + pp[1], y = yy[0] + yy[1];
;                             sa += dpp_f<0xB1>(sa); y += dpp_f<0xB1>(y);
;                             sa += dpp_f<0x4E>(sa); y += dpp_f<0x4E>(y);
;                             sa += dpp_f<0x141>(sa); y += dpp_f<0x141>(y);
;                             sa += dpp_f<0x140>(sa); y += dpp_f<0x140>(y);
;                             sY[((s - 1) & 31) * 16 + srow] = y;
;                             const f32x2 sv = {sa, sa};
;                             S01 = S01 * (f32x2){w_[0], w_[1]} + vv * (f32x2){k_[0], k_[1]};
;                             S23 = S23 * (f32x2){w_[2], w_[3]} + vv * (f32x2){k_[2], k_[3]};
;                             S01 = sv * (f32x2){b_[0], b_[1]} + S01;
;                             S23 = sv * (f32x2){b_[2], b_[3]} + S23;
;                             rp = r_;
;                             a_ = a_n; w_ = w_n; b_ = b_n; k_ = k_n; r_ = r_n;
;                         }
; #pragma unroll
;                         for (int u = 0; u < 4; ++u) vq[u] = vn[u];
;                     }
;                     { f32x2 yy = S01 * (f32x2){rp[0], rp[1]}; yy = S23 * (f32x2){rp[2], rp[3]} + yy; sY[31 * 16 + srow] = red16(yy[0] + yy[1]); }
;                     __builtin_amdgcn_s_setprio(0);
.LBB0_620:
	s_mov_b64 s[10:11], 0
	s_cmp_eq_u64 s[0:1], 0
	s_cbranch_scc0 .LBB0_594
	s_setprio 1
	s_mov_b32 s14, 0x3fff3fff
	s_mov_b32 s15, s14
	v_pk_mul_f32 v[114:115], v[166:167], v[22:23]
	v_pk_mul_f32 v[116:117], v[166:167], v[18:19]
	v_pk_fma_f32 v[114:115], v[164:165], v[24:25], v[114:115]
	v_pk_fma_f32 v[116:117], v[164:165], v[20:21], v[116:117]
	v_add_f32_e32 v122, v114, v115
	v_pk_mul_f32 v[118:119], v[110:111], v[34:35] op_sel:[1,0]
	v_add_f32_e32 v214, v116, v117
	v_add_f32_dpp v122, v122, v122 quad_perm:[1,0,3,2] row_mask:0xf bank_mask:0xf bound_ctrl:1
	v_pk_mul_f32 v[120:121], v[110:111], v[36:37] op_sel:[1,0]
	v_add_f32_dpp v204, v204, v204 row_mirror row_mask:0xf bank_mask:0xf bound_ctrl:1
	v_add_f32_dpp v122, v122, v122 quad_perm:[2,3,0,1] row_mask:0xf bank_mask:0xf bound_ctrl:1
	v_pk_fma_f32 v[166:167], v[166:167], v[26:27], v[118:119]
	v_add_f32_dpp v204, v212, v212 row_mirror row_mask:0xf bank_mask:0xc bound_ctrl:1
	v_add_f32_dpp v122, v122, v122 row_half_mirror row_mask:0xf bank_mask:0xf bound_ctrl:1
	v_pk_fma_f32 v[164:165], v[164:165], v[28:29], v[120:121]
	v_add_f32_dpp v205, v205, v205 row_mirror row_mask:0xf bank_mask:0xf bound_ctrl:1
	v_add_f32_dpp v122, v122, v122 row_mirror row_mask:0xf bank_mask:0xf bound_ctrl:1
	v_add_f32_dpp v205, v213, v213 row_mirror row_mask:0xf bank_mask:0xc bound_ctrl:1
	v_add_f32_dpp v206, v206, v206 row_mirror row_mask:0xf bank_mask:0xf bound_ctrl:1
	v_pk_fma_f32 v[166:167], v[30:31], v[122:123], v[166:167] op_sel_hi:[1,0,1]
	v_pk_fma_f32 v[164:165], v[32:33], v[122:123], v[164:165] op_sel_hi:[1,0,1]
	v_add_f32_dpp v206, v214, v214 row_mirror row_mask:0xf bank_mask:0xc bound_ctrl:1
	v_pk_mul_f32 v[114:115], v[166:167], v[42:43]
	v_pk_mul_f32 v[116:117], v[166:167], v[38:39]
	v_pk_fma_f32 v[114:115], v[164:165], v[44:45], v[114:115]
	v_pk_fma_f32 v[116:117], v[164:165], v[40:41], v[116:117]
	v_add_f32_e32 v122, v114, v115
	v_pk_mul_f32 v[118:119], v[112:113], v[54:55] op_sel_hi:[0,1]
	v_add_f32_e32 v215, v116, v117
	v_add_f32_dpp v122, v122, v122 quad_perm:[1,0,3,2] row_mask:0xf bank_mask:0xf bound_ctrl:1
	v_pk_mul_f32 v[120:121], v[112:113], v[56:57] op_sel_hi:[0,1]
	v_add_f32_dpp v207, v207, v207 row_mirror row_mask:0xf bank_mask:0xf bound_ctrl:1
	v_add_f32_dpp v122, v122, v122 quad_perm:[2,3,0,1] row_mask:0xf bank_mask:0xf bound_ctrl:1
	v_pk_fma_f32 v[166:167], v[166:167], v[46:47], v[118:119]
	v_add_f32_dpp v207, v215, v215 row_mirror row_mask:0xf bank_mask:0xc bound_ctrl:1
	v_add_f32_dpp v122, v122, v122 row_half_mirror row_mask:0xf bank_mask:0xf bound_ctrl:1
	v_pk_fma_f32 v[164:165], v[164:165], v[48:49], v[120:121]
	s_nop 0
	v_add_f32_dpp v122, v122, v122 row_mirror row_mask:0xf bank_mask:0xf bound_ctrl:1
	s_nop 0
	v_pk_fma_f32 v[166:167], v[50:51], v[122:123], v[166:167] op_sel_hi:[1,0,1]
	v_pk_fma_f32 v[164:165], v[52:53], v[122:123], v[164:165] op_sel_hi:[1,0,1]
	v_pk_mul_f32 v[114:115], v[166:167], v[62:63]
	v_pk_mul_f32 v[116:117], v[166:167], v[58:59]
	v_pk_fma_f32 v[114:115], v[164:165], v[64:65], v[114:115]
	v_pk_fma_f32 v[116:117], v[164:165], v[60:61], v[116:117]
	v_add_f32_e32 v122, v114, v115
	v_pk_mul_f32 v[118:119], v[112:113], v[74:75] op_sel:[1,0]
	v_add_f32_e32 v216, v116, v117
	v_add_f32_dpp v122, v122, v122 quad_perm:[1,0,3,2] row_mask:0xf bank_mask:0xf bound_ctrl:1
	v_pk_mul_f32 v[120:121], v[112:113], v[76:77] op_sel:[1,0]
	v_add_f32_dpp v208, v208, v208 row_mirror row_mask:0xf bank_mask:0xf bound_ctrl:1
	v_add_f32_dpp v122, v122, v122 quad_perm:[2,3,0,1] row_mask:0xf bank_mask:0xf bound_ctrl:1
	v_pk_fma_f32 v[166:167], v[166:167], v[66:67], v[118:119]
	v_add_f32_dpp v208, v216, v216 row_mirror row_mask:0xf bank_mask:0xc bound_ctrl:1
	v_add_f32_dpp v122, v122, v122 row_half_mirror row_mask:0xf bank_mask:0xf bound_ctrl:1
	v_pk_fma_f32 v[164:165], v[164:165], v[68:69], v[120:121]
	s_nop 0
	v_add_f32_dpp v122, v122, v122 row_mirror row_mask:0xf bank_mask:0xf bound_ctrl:1
	s_nop 0
	v_pk_fma_f32 v[166:167], v[70:71], v[122:123], v[166:167] op_sel_hi:[1,0,1]
	v_pk_fma_f32 v[164:165], v[72:73], v[122:123], v[164:165] op_sel_hi:[1,0,1]
	v_pk_mul_f32 v[116:117], v[166:167], v[78:79]
	s_nop 0
	v_pk_fma_f32 v[116:117], v[164:165], v[80:81], v[116:117]
	s_nop 0
	v_add_f32_e32 v217, v116, v117
	v_mov_b32_e32 v218, 0
	v_mov_b32_e32 v219, 0
	s_nop 1
	v_add_f32_dpp v209, v209, v209 row_mirror row_mask:0xf bank_mask:0xf bound_ctrl:1
	v_add_f32_dpp v209, v217, v217 row_mirror row_mask:0xf bank_mask:0xc bound_ctrl:1
	v_add_f32_dpp v210, v210, v210 row_mirror row_mask:0xf bank_mask:0xf bound_ctrl:1
	v_add_f32_dpp v210, v218, v218 row_mirror row_mask:0xf bank_mask:0xc bound_ctrl:1
	v_add_f32_dpp v211, v211, v211 row_mirror row_mask:0xf bank_mask:0xf bound_ctrl:1
	v_add_f32_dpp v211, v219, v219 row_mirror row_mask:0xf bank_mask:0xc bound_ctrl:1
	s_nop 1
	v_add_f32_dpp v204, v204, v204 row_half_mirror row_mask:0xf bank_mask:0xf bound_ctrl:1
	v_add_f32_dpp v205, v205, v205 row_half_mirror row_mask:0xf bank_mask:0xf bound_ctrl:1
	v_add_f32_dpp v206, v206, v206 row_half_mirror row_mask:0xf bank_mask:0xf bound_ctrl:1
	v_add_f32_dpp v207, v207, v207 row_half_mirror row_mask:0xf bank_mask:0xf bound_ctrl:1
	v_add_f32_dpp v204, v208, v208 row_half_mirror row_mask:0xf bank_mask:0xa bound_ctrl:1
	v_add_f32_dpp v205, v209, v209 row_half_mirror row_mask:0xf bank_mask:0xa bound_ctrl:1
	v_add_f32_dpp v206, v210, v210 row_half_mirror row_mask:0xf bank_mask:0xa bound_ctrl:1
	v_add_f32_dpp v207, v211, v211 row_half_mirror row_mask:0xf bank_mask:0xa bound_ctrl:1
	v_add_f32_dpp v204, v204, v204 quad_perm:[1,0,3,2] row_mask:0xf bank_mask:0xf bound_ctrl:1
	v_add_f32_dpp v205, v205, v205 quad_perm:[1,0,3,2] row_mask:0xf bank_mask:0xf bound_ctrl:1
	v_add_f32_dpp v206, v206, v206 quad_perm:[1,0,3,2] row_mask:0xf bank_mask:0xf bound_ctrl:1
	v_add_f32_dpp v207, v207, v207 quad_perm:[1,0,3,2] row_mask:0xf bank_mask:0xf bound_ctrl:1
	v_add_f32_dpp v204, v204, v204 quad_perm:[2,3,0,1] row_mask:0xf bank_mask:0xf bound_ctrl:1
	v_add_f32_dpp v205, v205, v205 quad_perm:[2,3,0,1] row_mask:0xf bank_mask:0xf bound_ctrl:1
	v_add_f32_dpp v206, v206, v206 quad_perm:[2,3,0,1] row_mask:0xf bank_mask:0xf bound_ctrl:1
	v_add_f32_dpp v207, v207, v207 quad_perm:[2,3,0,1] row_mask:0xf bank_mask:0xf bound_ctrl:1
	v_cndmask_b32_e64 v202, v204, v205, s[34:35]
	v_cndmask_b32_e64 v202, v202, v206, s[56:57]
	v_cndmask_b32_e64 v202, v202, v207, s[98:99]
	v_cvt_f16_f32_e32 v203, v202
	s_mov_b64 exec, s[14:15]
	global_store_short v[128:129], v203, off
	s_mov_b64 exec, -1
	v_lshl_add_u64 v[128:129], v[128:129], 0, s[100:101]
	s_setprio 0
	s_branch .LBB0_594
